# A1+E1+E2+E5+E4: EpiResid XB loads batched 2x8 (P5,P7); EpiMix gate rows cache-warmed by unused loads at epilogue start
# baseline (speedup 1.0000x reference)
; __device__ __forceinline__ float bf_lo(unsigned w) { return __uint_as_float(w << 16); }
; __device__ __forceinline__ float bf_hi(unsigned w) { return __uint_as_float(w & 0xffff0000u); }
;     __device__ __forceinline__ void operator()(f32x4 (&acc)[2][2][4][2], const pg8::Unit& u, int wr, int wc, int fr, int fq) const {
;         const int row0 = u.pm * 256 + wr * 64 + fr, col0 = u.pn * 256 + wc * 32 + 8 * fq;
; #pragma unroll
;         for (int ai = 0; ai < 2; ++ai)
; #pragma unroll
;             for (int m = 0; m < 4; ++m) { const size_t row = (size_t)(row0 + ai * 128 + m * 16);
; #pragma unroll
;                 for (int bj = 0; bj < 2; ++bj) { const int col = col0 + bj * 128;
;                     const u32x4 gw = *(const u32x4*)(proj + row * NPROJ + PC_MG + u.sub * D + col);
;                     float g[8] = {bf_lo(gw.x), bf_hi(gw.x), bf_lo(gw.y), bf_hi(gw.y), bf_lo(gw.z), bf_hi(gw.z), bf_lo(gw.w), bf_hi(gw.w)};
;                     if (u.sub < 2) { const u32x4 nw = *(const u32x4*)(proj + row * NPROJ + PC_MG + (u.sub + 1) * D + col);
.LBB0_1594:
	v_lshl_add_u32 v168, s74, 8, v147
	v_ashrrev_i32_e32 v169, 31, v168
	v_lshlrev_b64 v[134:135], 15, v[168:169]
	v_lshl_add_u64 v[134:135], s[62:63], 0, v[134:135]
	s_lshl_b32 s28, s30, 11
	v_lshl_or_b32 v4, s31, 8, v177
	v_lshl_add_u64 v[170:171], v[134:135], 0, s[52:53]
	s_ashr_i32 s29, s28, 31
	v_lshl_add_u64 v[134:135], s[28:29], 1, v[170:171]
	v_ashrrev_i32_e32 v5, 31, v4
	v_lshl_add_u64 v[174:175], v[4:5], 1, v[134:135]
	s_mov_b32 s101, 0
	global_load_dwordx4 v[212:215], v[174:175], off
	global_load_dwordx4 v[216:219], v[174:175], off offset:256
	s_mov_b32 s100, 0x1000
	v_lshl_add_u64 v[244:245], v[174:175], 0, s[100:101]
	global_load_dwordx4 v[212:215], v[244:245], off
	global_load_dwordx4 v[216:219], v[244:245], off offset:256
	s_mov_b32 s100, 0x80000
	v_lshl_add_u64 v[244:245], v[174:175], 0, s[100:101]
	global_load_dwordx4 v[212:215], v[244:245], off
	global_load_dwordx4 v[216:219], v[244:245], off offset:256
	s_mov_b32 s100, 0x81000
	v_lshl_add_u64 v[244:245], v[174:175], 0, s[100:101]
	global_load_dwordx4 v[212:215], v[244:245], off
	global_load_dwordx4 v[216:219], v[244:245], off offset:256
	s_mov_b32 s100, 0x100000
	v_lshl_add_u64 v[244:245], v[174:175], 0, s[100:101]
	global_load_dwordx4 v[212:215], v[244:245], off
	global_load_dwordx4 v[216:219], v[244:245], off offset:256
	s_mov_b32 s100, 0x101000
	v_lshl_add_u64 v[244:245], v[174:175], 0, s[100:101]
	global_load_dwordx4 v[212:215], v[244:245], off
	global_load_dwordx4 v[216:219], v[244:245], off offset:256
	s_mov_b32 s100, 0x180000
	v_lshl_add_u64 v[244:245], v[174:175], 0, s[100:101]
	global_load_dwordx4 v[212:215], v[244:245], off
	global_load_dwordx4 v[216:219], v[244:245], off offset:256
	s_mov_b32 s100, 0x181000
	v_lshl_add_u64 v[244:245], v[174:175], 0, s[100:101]
	global_load_dwordx4 v[212:215], v[244:245], off
	global_load_dwordx4 v[216:219], v[244:245], off offset:256
	s_mov_b32 s100, 0x400000
	v_lshl_add_u64 v[244:245], v[174:175], 0, s[100:101]
	global_load_dwordx4 v[212:215], v[244:245], off
	global_load_dwordx4 v[216:219], v[244:245], off offset:256
	s_mov_b32 s100, 0x401000
	v_lshl_add_u64 v[244:245], v[174:175], 0, s[100:101]
	global_load_dwordx4 v[212:215], v[244:245], off
	global_load_dwordx4 v[216:219], v[244:245], off offset:256
	s_mov_b32 s100, 0x480000
	v_lshl_add_u64 v[244:245], v[174:175], 0, s[100:101]
	global_load_dwordx4 v[212:215], v[244:245], off
	global_load_dwordx4 v[216:219], v[244:245], off offset:256
	s_mov_b32 s100, 0x481000
	v_lshl_add_u64 v[244:245], v[174:175], 0, s[100:101]
	global_load_dwordx4 v[212:215], v[244:245], off
	global_load_dwordx4 v[216:219], v[244:245], off offset:256
	s_mov_b32 s100, 0x500000
	v_lshl_add_u64 v[244:245], v[174:175], 0, s[100:101]
	global_load_dwordx4 v[212:215], v[244:245], off
	global_load_dwordx4 v[216:219], v[244:245], off offset:256
	s_mov_b32 s100, 0x501000
	v_lshl_add_u64 v[244:245], v[174:175], 0, s[100:101]
	global_load_dwordx4 v[212:215], v[244:245], off
	global_load_dwordx4 v[216:219], v[244:245], off offset:256
	s_mov_b32 s100, 0x580000
	v_lshl_add_u64 v[244:245], v[174:175], 0, s[100:101]
	global_load_dwordx4 v[212:215], v[244:245], off
	global_load_dwordx4 v[216:219], v[244:245], off offset:256
	s_mov_b32 s100, 0x581000
	v_lshl_add_u64 v[244:245], v[174:175], 0, s[100:101]
	global_load_dwordx4 v[212:215], v[244:245], off
	global_load_dwordx4 v[216:219], v[244:245], off offset:256
	global_load_dwordx4 v[138:141], v[174:175], off
	s_cmp_lt_i32 s30, 2
	s_cselect_b64 s[12:13], -1, 0
	s_cmp_gt_i32 s30, 1
	s_cselect_b64 s[30:31], -1, 0
	s_and_b64 vcc, exec, s[30:31]
	s_waitcnt vmcnt(0)
	v_lshlrev_b32_e32 v134, 16, v138
	v_and_b32_e32 v135, 0xffff0000, v138
	v_lshlrev_b32_e32 v136, 16, v139
	v_and_b32_e32 v137, 0xffff0000, v139
	v_lshlrev_b32_e32 v138, 16, v140
	v_and_b32_e32 v139, 0xffff0000, v140
	v_lshlrev_b32_e32 v140, 16, v141
	v_and_b32_e32 v141, 0xffff0000, v141
	s_cbranch_vccnz .LBB0_1596
	s_add_i32 s14, s28, 0x800
	s_ashr_i32 s15, s14, 31
	v_lshl_add_u64 v[172:173], s[14:15], 1, v[170:171]
	v_lshl_add_u64 v[172:173], v[4:5], 1, v[172:173]
	global_load_dwordx4 v[180:183], v[172:173], off
	s_waitcnt vmcnt(0)
	v_lshlrev_b32_e32 v3, 16, v180
	v_max_f32_e32 v3, v3, v3
	v_and_b32_e32 v173, 0xffff0000, v180
	v_max_f32_e32 v3, 0x358637bd, v3
	v_rcp_f32_e32 v172, v3
	v_max_f32_e32 v3, v173, v173
	v_max_f32_e32 v3, 0x358637bd, v3
	v_rcp_f32_e32 v173, v3
	v_lshlrev_b32_e32 v179, 16, v181
	v_max_f32_e32 v3, v179, v179
	v_and_b32_e32 v180, 0xffff0000, v181
	v_max_f32_e32 v3, 0x358637bd, v3
	v_pk_mul_f32 v[134:135], v[172:173], v[134:135]
	v_rcp_f32_e32 v172, v3
	v_max_f32_e32 v3, v180, v180
	v_max_f32_e32 v3, 0x358637bd, v3
	v_rcp_f32_e32 v173, v3
	v_lshlrev_b32_e32 v181, 16, v182
	v_max_f32_e32 v3, v181, v181
	v_and_b32_e32 v182, 0xffff0000, v182
	v_max_f32_e32 v3, 0x358637bd, v3
	v_pk_mul_f32 v[136:137], v[172:173], v[136:137]
	v_rcp_f32_e32 v172, v3
	v_max_f32_e32 v3, v182, v182
	v_max_f32_e32 v3, 0x358637bd, v3
	v_rcp_f32_e32 v173, v3
	v_lshlrev_b32_e32 v184, 16, v183
	v_max_f32_e32 v3, v184, v184
	v_and_b32_e32 v183, 0xffff0000, v183
	v_max_f32_e32 v3, 0x358637bd, v3
	v_pk_mul_f32 v[138:139], v[172:173], v[138:139]
	v_rcp_f32_e32 v172, v3
	v_max_f32_e32 v3, v183, v183
	v_max_f32_e32 v3, 0x358637bd, v3
	v_rcp_f32_e32 v173, v3
	s_nop 0
	v_pk_mul_f32 v[140:141], v[172:173], v[140:141]

; __device__ __forceinline__ unsigned cvt_pk_bf16(float lo, float hi) { const f32x2 v = {lo, hi}; return __builtin_bit_cast(unsigned, __builtin_convertvector(v, bf16x2_t)); }
; __device__ __forceinline__ float bf_lo(unsigned w) { return __uint_as_float(w << 16); }
; __device__ __forceinline__ float bf_hi(unsigned w) { return __uint_as_float(w & 0xffff0000u); }
;     __device__ __forceinline__ void operator()(const f32x4 (&acc)[2][2][4][2], const pg8::Unit& u, int wr, int wc, int fr, int fq) const {
;         const int row0 = u.pm * 256 + wr * 64 + fr, col0 = u.pn * 256 + wc * 32 + 8 * fq;
; #pragma unroll
;         for (int ai = 0; ai < 2; ++ai)
; #pragma unroll
;             for (int m = 0; m < 4; ++m) { const size_t row = (size_t)(row0 + ai * 128 + m * 16); float sq = 0.f;
; #pragma unroll
;                 for (int bj = 0; bj < 2; ++bj) { const int col = col0 + bj * 128; bf16_t* xp = XB + row * D + col; const u32x4 xo = *(const u32x4*)xp;
;                     const f32x4 v0 = acc[ai][bj][m][0] + (f32x4){bf_lo(xo.x), bf_hi(xo.x), bf_lo(xo.y), bf_hi(xo.y)}, v1 = acc[ai][bj][m][1] + (f32x4){bf_lo(xo.z), bf_hi(xo.z), bf_lo(xo.w), bf_hi(xo.w)};
;                     sq += (v0[0] * v0[0] + v0[1] * v0[1]) + (v0[2] * v0[2] + v0[3] * v0[3]) + (v1[0] * v1[0] + v1[1] * v1[1]) + (v1[2] * v1[2] + v1[3] * v1[3]);
;                     u32x4 w; w.x = cvt_pk_bf16(v0[0], v0[1]); w.y = cvt_pk_bf16(v0[2], v0[3]); w.z = cvt_pk_bf16(v1[0], v1[1]); w.w = cvt_pk_bf16(v1[2], v1[3]);
;                     *(u32x4*)xp = w; }
;                 sq += __shfl_xor(sq, 16); sq += __shfl_xor(sq, 32);
;                 if (fq == 0) ssq[row * 32 + u.pn * 4 + wc] = sq; }
.LBB0_1744:
	v_and_b32_e32 v161, 64, v196
	v_xor_b32_e32 v159, 16, v196
	v_add_u32_e32 v161, 64, v161
	v_cmp_lt_i32_e32 vcc, v159, v161
	v_lshl_add_u32 v160, s55, 8, v3
	v_lshl_or_b32 v158, s45, 8, v164
	v_cndmask_b32_e32 v159, v196, v159, vcc
	v_lshlrev_b32_e32 v167, 2, v159
	v_xor_b32_e32 v159, 32, v196
	v_cmp_lt_i32_e32 vcc, v159, v161
	v_ashrrev_i32_e32 v161, 31, v160
	v_lshlrev_b64 v[162:163], 12, v[160:161]
	v_cndmask_b32_e32 v159, v196, v159, vcc
	v_lshlrev_b32_e32 v166, 2, v159
	v_lshl_add_u64 v[162:163], s[56:57], 0, v[162:163]
	v_ashrrev_i32_e32 v159, 31, v158
	v_lshl_add_u64 v[162:163], v[158:159], 1, v[162:163]
	s_mov_b32 s101, 0
	global_load_dwordx4 v[212:215], v[162:163], off
	global_load_dwordx4 v[216:219], v[162:163], off offset:256
	s_mov_b32 s100, 0x10000
	v_lshl_add_u64 v[244:245], v[162:163], 0, s[100:101]
	global_load_dwordx4 v[220:223], v[244:245], off
	global_load_dwordx4 v[224:227], v[244:245], off offset:256
	s_mov_b32 s100, 0x20000
	v_lshl_add_u64 v[244:245], v[162:163], 0, s[100:101]
	global_load_dwordx4 v[228:231], v[244:245], off
	global_load_dwordx4 v[232:235], v[244:245], off offset:256
	s_mov_b32 s100, 0x30000
	v_lshl_add_u64 v[244:245], v[162:163], 0, s[100:101]
	global_load_dwordx4 v[236:239], v[244:245], off
	global_load_dwordx4 v[240:243], v[244:245], off offset:256
	s_waitcnt vmcnt(0)
	s_lshl_b32 s26, s45, 2
	s_ashr_i32 s27, s26, 31
	v_lshlrev_b32_e32 v172, 16, v212
	v_and_b32_e32 v173, 0xffff0000, v212
	v_lshlrev_b32_e32 v168, 16, v213
	v_and_b32_e32 v169, 0xffff0000, v213
	v_pk_add_f32 v[130:131], v[130:131], v[168:169]
	v_pk_add_f32 v[128:129], v[128:129], v[172:173]
	v_lshlrev_b32_e32 v168, 16, v214
	v_and_b32_e32 v169, 0xffff0000, v214
	v_lshlrev_b32_e32 v170, 16, v215
	v_and_b32_e32 v171, 0xffff0000, v215
	v_pk_add_f32 v[170:171], v[126:127], v[170:171]
	v_pk_add_f32 v[126:127], v[124:125], v[168:169]
	v_mul_f32_e32 v124, v129, v129
	v_mul_f32_e32 v125, v131, v131
	v_fmac_f32_e32 v124, v128, v128
	v_fmac_f32_e32 v125, v130, v130
	v_add_f32_e32 v124, v124, v125
	v_mul_f32_e32 v125, v127, v127
	v_fmac_f32_e32 v125, v126, v126
	v_add_f32_e32 v124, v125, v124
	v_mul_f32_e32 v125, v171, v171
	v_fmac_f32_e32 v125, v170, v170
	v_add_f32_e32 v168, v125, v124
	v_cvt_pk_bf16_f32 v124, v128, v129
	v_cvt_pk_bf16_f32 v125, v130, v131
	v_cvt_pk_bf16_f32 v126, v126, v127
	v_cvt_pk_bf16_f32 v127, v170, v171
	global_store_dwordx4 v[162:163], v[124:127], off
	v_lshlrev_b32_e32 v128, 16, v216
	v_and_b32_e32 v129, 0xffff0000, v216
	v_lshlrev_b32_e32 v124, 16, v217
	v_and_b32_e32 v125, 0xffff0000, v217
	v_pk_add_f32 v[122:123], v[122:123], v[124:125]
	v_pk_add_f32 v[120:121], v[120:121], v[128:129]
	v_lshlrev_b32_e32 v124, 16, v218
	v_and_b32_e32 v125, 0xffff0000, v218
	v_lshlrev_b32_e32 v126, 16, v219
	v_and_b32_e32 v127, 0xffff0000, v219
	v_pk_add_f32 v[126:127], v[118:119], v[126:127]
	v_pk_add_f32 v[118:119], v[116:117], v[124:125]
	v_mul_f32_e32 v116, v121, v121
	v_mul_f32_e32 v117, v123, v123
	v_fmac_f32_e32 v116, v120, v120
	v_fmac_f32_e32 v117, v122, v122
	v_add_f32_e32 v116, v116, v117
	v_mul_f32_e32 v117, v119, v119
	v_fmac_f32_e32 v117, v118, v118
	v_add_f32_e32 v116, v117, v116
	v_mul_f32_e32 v117, v127, v127
	v_fmac_f32_e32 v117, v126, v126
	v_add_f32_e32 v116, v117, v116
	v_add_f32_e32 v124, v168, v116
	v_cvt_pk_bf16_f32 v116, v120, v121
	v_cvt_pk_bf16_f32 v117, v122, v123
	v_cvt_pk_bf16_f32 v118, v118, v119
	v_cvt_pk_bf16_f32 v119, v126, v127
	global_store_dwordx4 v[162:163], v[116:119], off offset:256
	ds_bpermute_b32 v116, v167, v124
	s_waitcnt lgkmcnt(0)
	v_add_f32_e32 v116, v124, v116
	ds_bpermute_b32 v117, v166, v116
	s_and_saveexec_b64 s[28:29], s[10:11]
	s_cbranch_execz .LBB0_1746
	s_waitcnt lgkmcnt(0)
	v_add_f32_e32 v118, v116, v117
	v_lshlrev_b64 v[116:117], 7, v[160:161]
	v_lshl_add_u64 v[116:117], s[58:59], 0, v[116:117]
	v_lshl_add_u64 v[116:117], s[26:27], 2, v[116:117]
	s_lshl_b32 s80, s39, 2
	v_lshl_add_u64 v[116:117], v[116:117], 0, s[80:81]
	global_store_dword v[116:117], v118, off
.LBB0_1746:
	s_or_b64 exec, exec, s[28:29]
	v_or_b32_e32 v116, 16, v160
	s_waitcnt lgkmcnt(0)
	v_ashrrev_i32_e32 v117, 31, v116
	v_lshlrev_b64 v[118:119], 12, v[116:117]
	v_lshl_add_u64 v[118:119], s[56:57], 0, v[118:119]
	v_lshl_add_u64 v[118:119], v[158:159], 1, v[118:119]
	v_lshlrev_b32_e32 v124, 16, v220
	v_and_b32_e32 v125, 0xffff0000, v220
	v_lshlrev_b32_e32 v120, 16, v221
	v_and_b32_e32 v121, 0xffff0000, v221
	v_pk_add_f32 v[114:115], v[114:115], v[120:121]
	v_pk_add_f32 v[112:113], v[112:113], v[124:125]
	v_lshlrev_b32_e32 v120, 16, v222
	v_and_b32_e32 v121, 0xffff0000, v222
	v_lshlrev_b32_e32 v122, 16, v223
	v_and_b32_e32 v123, 0xffff0000, v223
	v_pk_add_f32 v[122:123], v[110:111], v[122:123]
	v_pk_add_f32 v[110:111], v[108:109], v[120:121]
	v_mul_f32_e32 v108, v113, v113
	v_mul_f32_e32 v109, v115, v115
	v_fmac_f32_e32 v108, v112, v112
	v_fmac_f32_e32 v109, v114, v114
	v_add_f32_e32 v108, v108, v109
	v_mul_f32_e32 v109, v111, v111
	v_fmac_f32_e32 v109, v110, v110
	v_add_f32_e32 v108, v109, v108
	v_mul_f32_e32 v109, v123, v123
	v_fmac_f32_e32 v109, v122, v122
	v_add_f32_e32 v120, v109, v108
	v_cvt_pk_bf16_f32 v108, v112, v113
	v_cvt_pk_bf16_f32 v109, v114, v115
	v_cvt_pk_bf16_f32 v110, v110, v111
	v_cvt_pk_bf16_f32 v111, v122, v123
	global_store_dwordx4 v[118:119], v[108:111], off
	v_lshlrev_b32_e32 v112, 16, v224
	v_and_b32_e32 v113, 0xffff0000, v224
	v_lshlrev_b32_e32 v108, 16, v225
	v_and_b32_e32 v109, 0xffff0000, v225
	v_pk_add_f32 v[106:107], v[106:107], v[108:109]
	v_pk_add_f32 v[104:105], v[104:105], v[112:113]
	v_lshlrev_b32_e32 v108, 16, v226
	v_and_b32_e32 v109, 0xffff0000, v226
	v_lshlrev_b32_e32 v110, 16, v227
	v_and_b32_e32 v111, 0xffff0000, v227
	v_pk_add_f32 v[110:111], v[102:103], v[110:111]
	v_pk_add_f32 v[102:103], v[100:101], v[108:109]
	v_mul_f32_e32 v100, v105, v105
	v_mul_f32_e32 v101, v107, v107
	v_fmac_f32_e32 v100, v104, v104
	v_fmac_f32_e32 v101, v106, v106
	v_add_f32_e32 v100, v100, v101
	v_mul_f32_e32 v101, v103, v103
	v_fmac_f32_e32 v101, v102, v102
	v_add_f32_e32 v100, v101, v100
	v_mul_f32_e32 v101, v111, v111
	v_fmac_f32_e32 v101, v110, v110
	v_add_f32_e32 v100, v101, v100
	v_add_f32_e32 v108, v120, v100
	v_cvt_pk_bf16_f32 v100, v104, v105
	v_cvt_pk_bf16_f32 v101, v106, v107
	v_cvt_pk_bf16_f32 v102, v102, v103
	v_cvt_pk_bf16_f32 v103, v110, v111
	global_store_dwordx4 v[118:119], v[100:103], off offset:256
	ds_bpermute_b32 v100, v167, v108
	s_waitcnt lgkmcnt(0)
	v_add_f32_e32 v100, v108, v100
	ds_bpermute_b32 v101, v166, v100
	s_and_saveexec_b64 s[28:29], s[10:11]
	s_cbranch_execz .LBB0_1748
	s_waitcnt lgkmcnt(0)
	v_add_f32_e32 v102, v100, v101
	v_lshlrev_b64 v[100:101], 7, v[116:117]
	v_lshl_add_u64 v[100:101], s[58:59], 0, v[100:101]
	v_lshl_add_u64 v[100:101], s[26:27], 2, v[100:101]
	s_lshl_b32 s80, s39, 2
	v_lshl_add_u64 v[100:101], v[100:101], 0, s[80:81]
	global_store_dword v[100:101], v102, off
; __device__ __forceinline__ unsigned cvt_pk_bf16(float lo, float hi) { const f32x2 v = {lo, hi}; return __builtin_bit_cast(unsigned, __builtin_convertvector(v, bf16x2_t)); }
; __device__ __forceinline__ float bf_lo(unsigned w) { return __uint_as_float(w << 16); }
; __device__ __forceinline__ float bf_hi(unsigned w) { return __uint_as_float(w & 0xffff0000u); }
;     __device__ __forceinline__ void operator()(const f32x4 (&acc)[2][2][4][2], const pg8::Unit& u, int wr, int wc, int fr, int fq) const {
;     ...
;             for (int m = 0; m < 4; ++m) { const size_t row = (size_t)(row0 + ai * 128 + m * 16); float sq = 0.f;
; #pragma unroll
;                 for (int bj = 0; bj < 2; ++bj) { const int col = col0 + bj * 128; bf16_t* xp = XB + row * D + col; const u32x4 xo = *(const u32x4*)xp;
;                     const f32x4 v0 = acc[ai][bj][m][0] + (f32x4){bf_lo(xo.x), bf_hi(xo.x), bf_lo(xo.y), bf_hi(xo.y)}, v1 = acc[ai][bj][m][1] + (f32x4){bf_lo(xo.z), bf_hi(xo.z), bf_lo(xo.w), bf_hi(xo.w)};
;                     sq += (v0[0] * v0[0] + v0[1] * v0[1]) + (v0[2] * v0[2] + v0[3] * v0[3]) + (v1[0] * v1[0] + v1[1] * v1[1]) + (v1[2] * v1[2] + v1[3] * v1[3]);
;                     u32x4 w; w.x = cvt_pk_bf16(v0[0], v0[1]); w.y = cvt_pk_bf16(v0[2], v0[3]); w.z = cvt_pk_bf16(v1[0], v1[1]); w.w = cvt_pk_bf16(v1[2], v1[3]);
;                     *(u32x4*)xp = w; }
;                 sq += __shfl_xor(sq, 16); sq += __shfl_xor(sq, 32);
;                 if (fq == 0) ssq[row * 32 + u.pn * 4 + wc] = sq; }
.LBB0_1748:
	s_or_b64 exec, exec, s[28:29]
	v_or_b32_e32 v100, 32, v160
	s_waitcnt lgkmcnt(0)
	v_ashrrev_i32_e32 v101, 31, v100
	v_lshlrev_b64 v[102:103], 12, v[100:101]
	v_lshl_add_u64 v[102:103], s[56:57], 0, v[102:103]
	v_lshl_add_u64 v[102:103], v[158:159], 1, v[102:103]
	v_lshlrev_b32_e32 v108, 16, v228
	v_and_b32_e32 v109, 0xffff0000, v228
	v_lshlrev_b32_e32 v104, 16, v229
	v_and_b32_e32 v105, 0xffff0000, v229
	v_pk_add_f32 v[98:99], v[98:99], v[104:105]
	v_pk_add_f32 v[96:97], v[96:97], v[108:109]
	v_lshlrev_b32_e32 v104, 16, v230
	v_and_b32_e32 v105, 0xffff0000, v230
	v_lshlrev_b32_e32 v106, 16, v231
	v_and_b32_e32 v107, 0xffff0000, v231
	v_pk_add_f32 v[106:107], v[94:95], v[106:107]
	v_pk_add_f32 v[94:95], v[92:93], v[104:105]
	v_mul_f32_e32 v92, v97, v97
	v_mul_f32_e32 v93, v99, v99
	v_fmac_f32_e32 v92, v96, v96
	v_fmac_f32_e32 v93, v98, v98
	v_add_f32_e32 v92, v92, v93
	v_mul_f32_e32 v93, v95, v95
	v_fmac_f32_e32 v93, v94, v94
	v_add_f32_e32 v92, v93, v92
	v_mul_f32_e32 v93, v107, v107
	v_fmac_f32_e32 v93, v106, v106
	v_add_f32_e32 v104, v93, v92
	v_cvt_pk_bf16_f32 v92, v96, v97
	v_cvt_pk_bf16_f32 v93, v98, v99
	v_cvt_pk_bf16_f32 v94, v94, v95
	v_cvt_pk_bf16_f32 v95, v106, v107
	global_store_dwordx4 v[102:103], v[92:95], off
	v_lshlrev_b32_e32 v96, 16, v232
	v_and_b32_e32 v97, 0xffff0000, v232
	v_lshlrev_b32_e32 v92, 16, v233
	v_and_b32_e32 v93, 0xffff0000, v233
	v_pk_add_f32 v[90:91], v[90:91], v[92:93]
	v_pk_add_f32 v[88:89], v[88:89], v[96:97]
	v_lshlrev_b32_e32 v92, 16, v234
	v_and_b32_e32 v93, 0xffff0000, v234
	v_lshlrev_b32_e32 v94, 16, v235
	v_and_b32_e32 v95, 0xffff0000, v235
	v_pk_add_f32 v[94:95], v[86:87], v[94:95]
	v_pk_add_f32 v[86:87], v[84:85], v[92:93]
	v_mul_f32_e32 v84, v89, v89
	v_mul_f32_e32 v85, v91, v91
	v_fmac_f32_e32 v84, v88, v88
	v_fmac_f32_e32 v85, v90, v90
	v_add_f32_e32 v84, v84, v85
	v_mul_f32_e32 v85, v87, v87
	v_fmac_f32_e32 v85, v86, v86
	v_add_f32_e32 v84, v85, v84
	v_mul_f32_e32 v85, v95, v95
	v_fmac_f32_e32 v85, v94, v94
	v_add_f32_e32 v84, v85, v84
	v_add_f32_e32 v92, v104, v84
	v_cvt_pk_bf16_f32 v84, v88, v89
	v_cvt_pk_bf16_f32 v85, v90, v91
	v_cvt_pk_bf16_f32 v86, v86, v87
	v_cvt_pk_bf16_f32 v87, v94, v95
	global_store_dwordx4 v[102:103], v[84:87], off offset:256
	ds_bpermute_b32 v84, v167, v92
	s_waitcnt lgkmcnt(0)
	v_add_f32_e32 v84, v92, v84
	ds_bpermute_b32 v85, v166, v84
	s_and_saveexec_b64 s[28:29], s[10:11]
	s_cbranch_execz .LBB0_1750
	s_waitcnt lgkmcnt(0)
	v_add_f32_e32 v86, v84, v85
	v_lshlrev_b64 v[84:85], 7, v[100:101]
	v_lshl_add_u64 v[84:85], s[58:59], 0, v[84:85]
	v_lshl_add_u64 v[84:85], s[26:27], 2, v[84:85]
	s_lshl_b32 s80, s39, 2
	v_lshl_add_u64 v[84:85], v[84:85], 0, s[80:81]
	global_store_dword v[84:85], v86, off
.LBB0_1750:
	s_or_b64 exec, exec, s[28:29]
	v_or_b32_e32 v84, 48, v160
	s_waitcnt lgkmcnt(0)
	v_ashrrev_i32_e32 v85, 31, v84
	v_lshlrev_b64 v[86:87], 12, v[84:85]
	v_lshl_add_u64 v[86:87], s[56:57], 0, v[86:87]
	v_lshl_add_u64 v[86:87], v[158:159], 1, v[86:87]
	v_lshlrev_b32_e32 v92, 16, v236
	v_and_b32_e32 v93, 0xffff0000, v236
	v_lshlrev_b32_e32 v88, 16, v237
	v_and_b32_e32 v89, 0xffff0000, v237
	v_pk_add_f32 v[82:83], v[82:83], v[88:89]
	v_pk_add_f32 v[80:81], v[80:81], v[92:93]
	v_lshlrev_b32_e32 v88, 16, v238
	v_and_b32_e32 v89, 0xffff0000, v238
	v_lshlrev_b32_e32 v90, 16, v239
	v_and_b32_e32 v91, 0xffff0000, v239
	v_pk_add_f32 v[90:91], v[78:79], v[90:91]
	v_pk_add_f32 v[78:79], v[76:77], v[88:89]
	v_mul_f32_e32 v76, v81, v81
	v_mul_f32_e32 v77, v83, v83
	v_fmac_f32_e32 v76, v80, v80
	v_fmac_f32_e32 v77, v82, v82
	v_add_f32_e32 v76, v76, v77
	v_mul_f32_e32 v77, v79, v79
	v_fmac_f32_e32 v77, v78, v78
	v_add_f32_e32 v76, v77, v76
	v_mul_f32_e32 v77, v91, v91
	v_fmac_f32_e32 v77, v90, v90
	v_add_f32_e32 v88, v77, v76
	v_cvt_pk_bf16_f32 v76, v80, v81
	v_cvt_pk_bf16_f32 v77, v82, v83
	v_cvt_pk_bf16_f32 v78, v78, v79
	v_cvt_pk_bf16_f32 v79, v90, v91
	global_store_dwordx4 v[86:87], v[76:79], off
	v_lshlrev_b32_e32 v80, 16, v240
	v_and_b32_e32 v81, 0xffff0000, v240
	v_lshlrev_b32_e32 v76, 16, v241
	v_and_b32_e32 v77, 0xffff0000, v241
	v_pk_add_f32 v[74:75], v[74:75], v[76:77]
	v_pk_add_f32 v[72:73], v[72:73], v[80:81]
	v_lshlrev_b32_e32 v76, 16, v242
	v_and_b32_e32 v77, 0xffff0000, v242
	v_lshlrev_b32_e32 v78, 16, v243
	v_and_b32_e32 v79, 0xffff0000, v243
	v_pk_add_f32 v[78:79], v[70:71], v[78:79]
	v_pk_add_f32 v[70:71], v[68:69], v[76:77]
	v_mul_f32_e32 v68, v73, v73
	v_mul_f32_e32 v69, v75, v75
	v_fmac_f32_e32 v68, v72, v72
	v_fmac_f32_e32 v69, v74, v74
	v_add_f32_e32 v68, v68, v69
	v_mul_f32_e32 v69, v71, v71
	v_fmac_f32_e32 v69, v70, v70
	v_add_f32_e32 v68, v69, v68
	v_mul_f32_e32 v69, v79, v79
	v_fmac_f32_e32 v69, v78, v78
	v_add_f32_e32 v68, v69, v68
	v_add_f32_e32 v76, v88, v68
	v_cvt_pk_bf16_f32 v68, v72, v73
	v_cvt_pk_bf16_f32 v69, v74, v75
	v_cvt_pk_bf16_f32 v70, v70, v71
	v_cvt_pk_bf16_f32 v71, v78, v79
	global_store_dwordx4 v[86:87], v[68:71], off offset:256
	ds_bpermute_b32 v68, v167, v76
	s_waitcnt lgkmcnt(0)
	v_add_f32_e32 v68, v76, v68
	ds_bpermute_b32 v69, v166, v68
	s_and_saveexec_b64 s[28:29], s[10:11]
	s_cbranch_execz .LBB0_1752
	s_waitcnt lgkmcnt(0)
	v_add_f32_e32 v70, v68, v69
	v_lshlrev_b64 v[68:69], 7, v[84:85]
	v_lshl_add_u64 v[68:69], s[58:59], 0, v[68:69]
	v_lshl_add_u64 v[68:69], s[26:27], 2, v[68:69]
	s_lshl_b32 s80, s39, 2
	v_lshl_add_u64 v[68:69], v[68:69], 0, s[80:81]
	global_store_dword v[68:69], v70, off
; __device__ __forceinline__ unsigned cvt_pk_bf16(float lo, float hi) { const f32x2 v = {lo, hi}; return __builtin_bit_cast(unsigned, __builtin_convertvector(v, bf16x2_t)); }
; __device__ __forceinline__ float bf_lo(unsigned w) { return __uint_as_float(w << 16); }
; __device__ __forceinline__ float bf_hi(unsigned w) { return __uint_as_float(w & 0xffff0000u); }
;     __device__ __forceinline__ void operator()(const f32x4 (&acc)[2][2][4][2], const pg8::Unit& u, int wr, int wc, int fr, int fq) const {
;         const int row0 = u.pm * 256 + wr * 64 + fr, col0 = u.pn * 256 + wc * 32 + 8 * fq;
; #pragma unroll
;         for (int ai = 0; ai < 2; ++ai)
; #pragma unroll
;             for (int m = 0; m < 4; ++m) { const size_t row = (size_t)(row0 + ai * 128 + m * 16); float sq = 0.f;
; #pragma unroll
;                 for (int bj = 0; bj < 2; ++bj) { const int col = col0 + bj * 128; bf16_t* xp = XB + row * D + col; const u32x4 xo = *(const u32x4*)xp;
;                     const f32x4 v0 = acc[ai][bj][m][0] + (f32x4){bf_lo(xo.x), bf_hi(xo.x), bf_lo(xo.y), bf_hi(xo.y)}, v1 = acc[ai][bj][m][1] + (f32x4){bf_lo(xo.z), bf_hi(xo.z), bf_lo(xo.w), bf_hi(xo.w)};
;                     sq += (v0[0] * v0[0] + v0[1] * v0[1]) + (v0[2] * v0[2] + v0[3] * v0[3]) + (v1[0] * v1[0] + v1[1] * v1[1]) + (v1[2] * v1[2] + v1[3] * v1[3]);
;                     u32x4 w; w.x = cvt_pk_bf16(v0[0], v0[1]); w.y = cvt_pk_bf16(v0[2], v0[3]); w.z = cvt_pk_bf16(v1[0], v1[1]); w.w = cvt_pk_bf16(v1[2], v1[3]);
;                     *(u32x4*)xp = w; }
;                 sq += __shfl_xor(sq, 16); sq += __shfl_xor(sq, 32);
;                 if (fq == 0) ssq[row * 32 + u.pn * 4 + wc] = sq; }
.LBB0_1752:
	s_or_b64 exec, exec, s[28:29]
	v_add_u32_e32 v68, 0x80, v160
	s_waitcnt lgkmcnt(0)
	v_ashrrev_i32_e32 v69, 31, v68
	v_lshlrev_b64 v[70:71], 12, v[68:69]
	v_lshl_add_u64 v[70:71], s[56:57], 0, v[70:71]
	v_lshl_add_u64 v[70:71], v[158:159], 1, v[70:71]
	s_mov_b32 s101, 0
	global_load_dwordx4 v[212:215], v[70:71], off
	global_load_dwordx4 v[216:219], v[70:71], off offset:256
	s_mov_b32 s100, 0x10000
	v_lshl_add_u64 v[244:245], v[70:71], 0, s[100:101]
	global_load_dwordx4 v[220:223], v[244:245], off
	global_load_dwordx4 v[224:227], v[244:245], off offset:256
	s_mov_b32 s100, 0x20000
	v_lshl_add_u64 v[244:245], v[70:71], 0, s[100:101]
	global_load_dwordx4 v[228:231], v[244:245], off
	global_load_dwordx4 v[232:235], v[244:245], off offset:256
	s_mov_b32 s100, 0x30000
	v_lshl_add_u64 v[244:245], v[70:71], 0, s[100:101]
	global_load_dwordx4 v[236:239], v[244:245], off
	global_load_dwordx4 v[240:243], v[244:245], off offset:256
	s_waitcnt vmcnt(0)
	v_lshlrev_b32_e32 v76, 16, v212
	v_and_b32_e32 v77, 0xffff0000, v212
	v_lshlrev_b32_e32 v72, 16, v213
	v_and_b32_e32 v73, 0xffff0000, v213
	v_pk_add_f32 v[66:67], v[66:67], v[72:73]
	v_pk_add_f32 v[64:65], v[64:65], v[76:77]
	v_lshlrev_b32_e32 v72, 16, v214
	v_and_b32_e32 v73, 0xffff0000, v214
	v_lshlrev_b32_e32 v74, 16, v215
	v_and_b32_e32 v75, 0xffff0000, v215
	v_pk_add_f32 v[74:75], v[62:63], v[74:75]
	v_pk_add_f32 v[62:63], v[60:61], v[72:73]
	v_mul_f32_e32 v60, v65, v65
	v_mul_f32_e32 v61, v67, v67
	v_fmac_f32_e32 v60, v64, v64
	v_fmac_f32_e32 v61, v66, v66
	v_add_f32_e32 v60, v60, v61
	v_mul_f32_e32 v61, v63, v63
	v_fmac_f32_e32 v61, v62, v62
	v_add_f32_e32 v60, v61, v60
	v_mul_f32_e32 v61, v75, v75
	v_fmac_f32_e32 v61, v74, v74
	v_add_f32_e32 v72, v61, v60
	v_cvt_pk_bf16_f32 v60, v64, v65
	v_cvt_pk_bf16_f32 v61, v66, v67
	v_cvt_pk_bf16_f32 v62, v62, v63
	v_cvt_pk_bf16_f32 v63, v74, v75
	global_store_dwordx4 v[70:71], v[60:63], off
	v_lshlrev_b32_e32 v64, 16, v216
	v_and_b32_e32 v65, 0xffff0000, v216
	v_lshlrev_b32_e32 v60, 16, v217
	v_and_b32_e32 v61, 0xffff0000, v217
	v_pk_add_f32 v[58:59], v[58:59], v[60:61]
	v_pk_add_f32 v[56:57], v[56:57], v[64:65]
	v_lshlrev_b32_e32 v60, 16, v218
	v_and_b32_e32 v61, 0xffff0000, v218
	v_lshlrev_b32_e32 v62, 16, v219
	v_and_b32_e32 v63, 0xffff0000, v219
	v_pk_add_f32 v[62:63], v[54:55], v[62:63]
	v_pk_add_f32 v[54:55], v[52:53], v[60:61]
	v_mul_f32_e32 v52, v57, v57
	v_mul_f32_e32 v53, v59, v59
	v_fmac_f32_e32 v52, v56, v56
	v_fmac_f32_e32 v53, v58, v58
	v_add_f32_e32 v52, v52, v53
	v_mul_f32_e32 v53, v55, v55
	v_fmac_f32_e32 v53, v54, v54
	v_add_f32_e32 v52, v53, v52
	v_mul_f32_e32 v53, v63, v63
	v_fmac_f32_e32 v53, v62, v62
	v_add_f32_e32 v52, v53, v52
	v_add_f32_e32 v60, v72, v52
	v_cvt_pk_bf16_f32 v52, v56, v57
	v_cvt_pk_bf16_f32 v53, v58, v59
	v_cvt_pk_bf16_f32 v54, v54, v55
	v_cvt_pk_bf16_f32 v55, v62, v63
	global_store_dwordx4 v[70:71], v[52:55], off offset:256
	ds_bpermute_b32 v52, v167, v60
	s_waitcnt lgkmcnt(0)
	v_add_f32_e32 v52, v60, v52
	ds_bpermute_b32 v53, v166, v52
	s_and_saveexec_b64 s[28:29], s[10:11]
	s_cbranch_execz .LBB0_1754
	s_waitcnt lgkmcnt(0)
	v_add_f32_e32 v54, v52, v53
	v_lshlrev_b64 v[52:53], 7, v[68:69]
	v_lshl_add_u64 v[52:53], s[58:59], 0, v[52:53]
	v_lshl_add_u64 v[52:53], s[26:27], 2, v[52:53]
	s_lshl_b32 s80, s39, 2
	v_lshl_add_u64 v[52:53], v[52:53], 0, s[80:81]
	global_store_dword v[52:53], v54, off
.LBB0_1754:
	s_or_b64 exec, exec, s[28:29]
	v_add_u32_e32 v52, 0x90, v160
	s_waitcnt lgkmcnt(0)
	v_ashrrev_i32_e32 v53, 31, v52
	v_lshlrev_b64 v[54:55], 12, v[52:53]
	v_lshl_add_u64 v[54:55], s[56:57], 0, v[54:55]
	v_lshl_add_u64 v[54:55], v[158:159], 1, v[54:55]
	v_lshlrev_b32_e32 v60, 16, v220
	v_and_b32_e32 v61, 0xffff0000, v220
	v_lshlrev_b32_e32 v56, 16, v221
	v_and_b32_e32 v57, 0xffff0000, v221
	v_pk_add_f32 v[50:51], v[50:51], v[56:57]
	v_pk_add_f32 v[48:49], v[48:49], v[60:61]
	v_lshlrev_b32_e32 v56, 16, v222
	v_and_b32_e32 v57, 0xffff0000, v222
	v_lshlrev_b32_e32 v58, 16, v223
	v_and_b32_e32 v59, 0xffff0000, v223
	v_pk_add_f32 v[58:59], v[46:47], v[58:59]
	v_pk_add_f32 v[46:47], v[44:45], v[56:57]
	v_mul_f32_e32 v44, v49, v49
	v_mul_f32_e32 v45, v51, v51
	v_fmac_f32_e32 v44, v48, v48
	v_fmac_f32_e32 v45, v50, v50
	v_add_f32_e32 v44, v44, v45
	v_mul_f32_e32 v45, v47, v47
	v_fmac_f32_e32 v45, v46, v46
	v_add_f32_e32 v44, v45, v44
	v_mul_f32_e32 v45, v59, v59
	v_fmac_f32_e32 v45, v58, v58
	v_add_f32_e32 v56, v45, v44
	v_cvt_pk_bf16_f32 v44, v48, v49
	v_cvt_pk_bf16_f32 v45, v50, v51
	v_cvt_pk_bf16_f32 v46, v46, v47
	v_cvt_pk_bf16_f32 v47, v58, v59
	global_store_dwordx4 v[54:55], v[44:47], off
	v_lshlrev_b32_e32 v48, 16, v224
	v_and_b32_e32 v49, 0xffff0000, v224
	v_lshlrev_b32_e32 v44, 16, v225
	v_and_b32_e32 v45, 0xffff0000, v225
	v_pk_add_f32 v[42:43], v[42:43], v[44:45]
	v_pk_add_f32 v[40:41], v[40:41], v[48:49]
	v_lshlrev_b32_e32 v44, 16, v226
	v_and_b32_e32 v45, 0xffff0000, v226
	v_lshlrev_b32_e32 v46, 16, v227
	v_and_b32_e32 v47, 0xffff0000, v227
	v_pk_add_f32 v[46:47], v[38:39], v[46:47]
	v_pk_add_f32 v[38:39], v[36:37], v[44:45]
	v_mul_f32_e32 v36, v41, v41
	v_mul_f32_e32 v37, v43, v43
	v_fmac_f32_e32 v36, v40, v40
	v_fmac_f32_e32 v37, v42, v42
	v_add_f32_e32 v36, v36, v37
	v_mul_f32_e32 v37, v39, v39
	v_fmac_f32_e32 v37, v38, v38
	v_add_f32_e32 v36, v37, v36
	v_mul_f32_e32 v37, v47, v47
	v_fmac_f32_e32 v37, v46, v46
	v_add_f32_e32 v36, v37, v36
	v_add_f32_e32 v44, v56, v36
	v_cvt_pk_bf16_f32 v36, v40, v41
	v_cvt_pk_bf16_f32 v37, v42, v43
	v_cvt_pk_bf16_f32 v38, v38, v39
	v_cvt_pk_bf16_f32 v39, v46, v47
	global_store_dwordx4 v[54:55], v[36:39], off offset:256
	ds_bpermute_b32 v36, v167, v44
	s_waitcnt lgkmcnt(0)
	v_add_f32_e32 v36, v44, v36
	ds_bpermute_b32 v37, v166, v36
	s_and_saveexec_b64 s[28:29], s[10:11]
	s_cbranch_execz .LBB0_1756
	s_waitcnt lgkmcnt(0)
	v_add_f32_e32 v38, v36, v37
	v_lshlrev_b64 v[36:37], 7, v[52:53]
	v_lshl_add_u64 v[36:37], s[58:59], 0, v[36:37]
	v_lshl_add_u64 v[36:37], s[26:27], 2, v[36:37]
	s_lshl_b32 s80, s39, 2
	v_lshl_add_u64 v[36:37], v[36:37], 0, s[80:81]
	global_store_dword v[36:37], v38, off
; __device__ __forceinline__ unsigned cvt_pk_bf16(float lo, float hi) { const f32x2 v = {lo, hi}; return __builtin_bit_cast(unsigned, __builtin_convertvector(v, bf16x2_t)); }
; __device__ __forceinline__ float bf_lo(unsigned w) { return __uint_as_float(w << 16); }
; __device__ __forceinline__ float bf_hi(unsigned w) { return __uint_as_float(w & 0xffff0000u); }
;     __device__ __forceinline__ void operator()(const f32x4 (&acc)[2][2][4][2], const pg8::Unit& u, int wr, int wc, int fr, int fq) const {
;     ...
;             for (int m = 0; m < 4; ++m) { const size_t row = (size_t)(row0 + ai * 128 + m * 16); float sq = 0.f;
; #pragma unroll
;                 for (int bj = 0; bj < 2; ++bj) { const int col = col0 + bj * 128; bf16_t* xp = XB + row * D + col; const u32x4 xo = *(const u32x4*)xp;
;                     const f32x4 v0 = acc[ai][bj][m][0] + (f32x4){bf_lo(xo.x), bf_hi(xo.x), bf_lo(xo.y), bf_hi(xo.y)}, v1 = acc[ai][bj][m][1] + (f32x4){bf_lo(xo.z), bf_hi(xo.z), bf_lo(xo.w), bf_hi(xo.w)};
;                     sq += (v0[0] * v0[0] + v0[1] * v0[1]) + (v0[2] * v0[2] + v0[3] * v0[3]) + (v1[0] * v1[0] + v1[1] * v1[1]) + (v1[2] * v1[2] + v1[3] * v1[3]);
;                     u32x4 w; w.x = cvt_pk_bf16(v0[0], v0[1]); w.y = cvt_pk_bf16(v0[2], v0[3]); w.z = cvt_pk_bf16(v1[0], v1[1]); w.w = cvt_pk_bf16(v1[2], v1[3]);
;                     *(u32x4*)xp = w; }
;                 sq += __shfl_xor(sq, 16); sq += __shfl_xor(sq, 32);
;                 if (fq == 0) ssq[row * 32 + u.pn * 4 + wc] = sq; }
.LBB0_1756:
	s_or_b64 exec, exec, s[28:29]
	v_add_u32_e32 v36, 0xa0, v160
	s_waitcnt lgkmcnt(0)
	v_ashrrev_i32_e32 v37, 31, v36
	v_lshlrev_b64 v[38:39], 12, v[36:37]
	v_lshl_add_u64 v[38:39], s[56:57], 0, v[38:39]
	v_lshl_add_u64 v[38:39], v[158:159], 1, v[38:39]
	v_lshlrev_b32_e32 v44, 16, v228
	v_and_b32_e32 v45, 0xffff0000, v228
	v_lshlrev_b32_e32 v40, 16, v229
	v_and_b32_e32 v41, 0xffff0000, v229
	v_pk_add_f32 v[34:35], v[34:35], v[40:41]
	v_pk_add_f32 v[32:33], v[32:33], v[44:45]
	v_lshlrev_b32_e32 v40, 16, v230
	v_and_b32_e32 v41, 0xffff0000, v230
	v_lshlrev_b32_e32 v42, 16, v231
	v_and_b32_e32 v43, 0xffff0000, v231
	v_pk_add_f32 v[42:43], v[30:31], v[42:43]
	v_pk_add_f32 v[30:31], v[28:29], v[40:41]
	v_mul_f32_e32 v28, v33, v33
	v_mul_f32_e32 v29, v35, v35
	v_fmac_f32_e32 v28, v32, v32
	v_fmac_f32_e32 v29, v34, v34
	v_add_f32_e32 v28, v28, v29
	v_mul_f32_e32 v29, v31, v31
	v_fmac_f32_e32 v29, v30, v30
	v_add_f32_e32 v28, v29, v28
	v_mul_f32_e32 v29, v43, v43
	v_fmac_f32_e32 v29, v42, v42
	v_add_f32_e32 v40, v29, v28
	v_cvt_pk_bf16_f32 v28, v32, v33
	v_cvt_pk_bf16_f32 v29, v34, v35
	v_cvt_pk_bf16_f32 v30, v30, v31
	v_cvt_pk_bf16_f32 v31, v42, v43
	global_store_dwordx4 v[38:39], v[28:31], off
	v_lshlrev_b32_e32 v32, 16, v232
	v_and_b32_e32 v33, 0xffff0000, v232
	v_lshlrev_b32_e32 v28, 16, v233
	v_and_b32_e32 v29, 0xffff0000, v233
	v_pk_add_f32 v[26:27], v[26:27], v[28:29]
	v_pk_add_f32 v[24:25], v[24:25], v[32:33]
	v_lshlrev_b32_e32 v28, 16, v234
	v_and_b32_e32 v29, 0xffff0000, v234
	v_lshlrev_b32_e32 v30, 16, v235
	v_and_b32_e32 v31, 0xffff0000, v235
	v_pk_add_f32 v[30:31], v[22:23], v[30:31]
	v_pk_add_f32 v[22:23], v[20:21], v[28:29]
	v_mul_f32_e32 v20, v25, v25
	v_mul_f32_e32 v21, v27, v27
	v_fmac_f32_e32 v20, v24, v24
	v_fmac_f32_e32 v21, v26, v26
	v_add_f32_e32 v20, v20, v21
	v_mul_f32_e32 v21, v23, v23
	v_fmac_f32_e32 v21, v22, v22
	v_add_f32_e32 v20, v21, v20
	v_mul_f32_e32 v21, v31, v31
	v_fmac_f32_e32 v21, v30, v30
	v_add_f32_e32 v20, v21, v20
	v_add_f32_e32 v28, v40, v20
	v_cvt_pk_bf16_f32 v20, v24, v25
	v_cvt_pk_bf16_f32 v21, v26, v27
	v_cvt_pk_bf16_f32 v22, v22, v23
	v_cvt_pk_bf16_f32 v23, v30, v31
	global_store_dwordx4 v[38:39], v[20:23], off offset:256
	ds_bpermute_b32 v20, v167, v28
	s_waitcnt lgkmcnt(0)
	v_add_f32_e32 v20, v28, v20
	ds_bpermute_b32 v21, v166, v20
	s_and_saveexec_b64 s[28:29], s[10:11]
	s_cbranch_execz .LBB0_1758
	s_waitcnt lgkmcnt(0)
	v_add_f32_e32 v22, v20, v21
	v_lshlrev_b64 v[20:21], 7, v[36:37]
	v_lshl_add_u64 v[20:21], s[58:59], 0, v[20:21]
	v_lshl_add_u64 v[20:21], s[26:27], 2, v[20:21]
	s_lshl_b32 s80, s39, 2
	v_lshl_add_u64 v[20:21], v[20:21], 0, s[80:81]
	global_store_dword v[20:21], v22, off
.LBB0_1758:
	s_or_b64 exec, exec, s[28:29]
	v_add_u32_e32 v20, 0xb0, v160
	s_waitcnt lgkmcnt(0)
	v_ashrrev_i32_e32 v21, 31, v20
	v_lshlrev_b64 v[22:23], 12, v[20:21]
	v_lshl_add_u64 v[22:23], s[56:57], 0, v[22:23]
	v_lshl_add_u64 v[22:23], v[158:159], 1, v[22:23]
	v_lshlrev_b32_e32 v28, 16, v236
	v_and_b32_e32 v29, 0xffff0000, v236
	v_lshlrev_b32_e32 v24, 16, v237
	v_and_b32_e32 v25, 0xffff0000, v237
	v_pk_add_f32 v[18:19], v[18:19], v[24:25]
	v_pk_add_f32 v[16:17], v[16:17], v[28:29]
	v_lshlrev_b32_e32 v24, 16, v238
	v_and_b32_e32 v25, 0xffff0000, v238
	v_lshlrev_b32_e32 v26, 16, v239
	v_and_b32_e32 v27, 0xffff0000, v239
	v_pk_add_f32 v[26:27], v[14:15], v[26:27]
	v_pk_add_f32 v[14:15], v[12:13], v[24:25]
	v_mul_f32_e32 v12, v17, v17
	v_mul_f32_e32 v13, v19, v19
	v_fmac_f32_e32 v12, v16, v16
	v_fmac_f32_e32 v13, v18, v18
	v_add_f32_e32 v12, v12, v13
	v_mul_f32_e32 v13, v15, v15
	v_fmac_f32_e32 v13, v14, v14
	v_add_f32_e32 v12, v13, v12
	v_mul_f32_e32 v13, v27, v27
	v_fmac_f32_e32 v13, v26, v26
	v_add_f32_e32 v24, v13, v12
	v_cvt_pk_bf16_f32 v12, v16, v17
	v_cvt_pk_bf16_f32 v13, v18, v19
	v_cvt_pk_bf16_f32 v14, v14, v15
	v_cvt_pk_bf16_f32 v15, v26, v27
	global_store_dwordx4 v[22:23], v[12:15], off
	v_lshlrev_b32_e32 v16, 16, v240
	v_and_b32_e32 v17, 0xffff0000, v240
	v_lshlrev_b32_e32 v12, 16, v241
	v_and_b32_e32 v13, 0xffff0000, v241
	v_pk_add_f32 v[10:11], v[10:11], v[12:13]
	v_pk_add_f32 v[8:9], v[8:9], v[16:17]
	v_lshlrev_b32_e32 v12, 16, v242
	v_and_b32_e32 v13, 0xffff0000, v242
	v_lshlrev_b32_e32 v14, 16, v243
	v_and_b32_e32 v15, 0xffff0000, v243
	v_pk_add_f32 v[14:15], v[6:7], v[14:15]
	v_pk_add_f32 v[6:7], v[4:5], v[12:13]
	v_mul_f32_e32 v4, v9, v9
	v_mul_f32_e32 v5, v11, v11
	v_fmac_f32_e32 v4, v8, v8
	v_fmac_f32_e32 v5, v10, v10
	v_add_f32_e32 v4, v4, v5
	v_mul_f32_e32 v5, v7, v7
	v_fmac_f32_e32 v5, v6, v6
	v_add_f32_e32 v4, v5, v4
	v_mul_f32_e32 v5, v15, v15
	v_fmac_f32_e32 v5, v14, v14
	v_add_f32_e32 v4, v5, v4
	v_add_f32_e32 v12, v24, v4
	v_cvt_pk_bf16_f32 v4, v8, v9
	v_cvt_pk_bf16_f32 v5, v10, v11
	v_cvt_pk_bf16_f32 v6, v6, v7
	v_cvt_pk_bf16_f32 v7, v14, v15
	global_store_dwordx4 v[22:23], v[4:7], off offset:256
	ds_bpermute_b32 v4, v167, v12
	s_waitcnt lgkmcnt(0)
	v_add_f32_e32 v4, v12, v4
	ds_bpermute_b32 v5, v166, v4
	s_and_saveexec_b64 s[28:29], s[10:11]
	s_cbranch_execz .LBB0_1760
	s_waitcnt lgkmcnt(0)
	v_add_f32_e32 v6, v4, v5
	v_lshlrev_b64 v[4:5], 7, v[20:21]
	v_lshl_add_u64 v[4:5], s[58:59], 0, v[4:5]
	v_lshl_add_u64 v[4:5], s[26:27], 2, v[4:5]
	s_lshl_b32 s80, s39, 2
	v_lshl_add_u64 v[4:5], v[4:5], 0, s[80:81]
	global_store_dword v[4:5], v6, off

; __device__ __forceinline__ unsigned cvt_pk_bf16(float lo, float hi) { const f32x2 v = {lo, hi}; return __builtin_bit_cast(unsigned, __builtin_convertvector(v, bf16x2_t)); }
; __device__ __forceinline__ float bf_lo(unsigned w) { return __uint_as_float(w << 16); }
; __device__ __forceinline__ float bf_hi(unsigned w) { return __uint_as_float(w & 0xffff0000u); }
;     __device__ __forceinline__ void operator()(const f32x4 (&acc)[2][2][4][2], const pg8::Unit& u, int wr, int wc, int fr, int fq) const {
;         const int row0 = u.pm * 256 + wr * 64 + fr, col0 = u.pn * 256 + wc * 32 + 8 * fq;
; #pragma unroll
;         for (int ai = 0; ai < 2; ++ai)
; #pragma unroll
;             for (int m = 0; m < 4; ++m) { const size_t row = (size_t)(row0 + ai * 128 + m * 16); float sq = 0.f;
; #pragma unroll
;                 for (int bj = 0; bj < 2; ++bj) { const int col = col0 + bj * 128; bf16_t* xp = XB + row * D + col; const u32x4 xo = *(const u32x4*)xp;
;                     const f32x4 v0 = acc[ai][bj][m][0] + (f32x4){bf_lo(xo.x), bf_hi(xo.x), bf_lo(xo.y), bf_hi(xo.y)}, v1 = acc[ai][bj][m][1] + (f32x4){bf_lo(xo.z), bf_hi(xo.z), bf_lo(xo.w), bf_hi(xo.w)};
;                     sq += (v0[0] * v0[0] + v0[1] * v0[1]) + (v0[2] * v0[2] + v0[3] * v0[3]) + (v1[0] * v1[0] + v1[1] * v1[1]) + (v1[2] * v1[2] + v1[3] * v1[3]);
;                     u32x4 w; w.x = cvt_pk_bf16(v0[0], v0[1]); w.y = cvt_pk_bf16(v0[2], v0[3]); w.z = cvt_pk_bf16(v1[0], v1[1]); w.w = cvt_pk_bf16(v1[2], v1[3]);
;                     *(u32x4*)xp = w; }
;                 sq += __shfl_xor(sq, 16); sq += __shfl_xor(sq, 32);
;                 if (fq == 0) ssq[row * 32 + u.pn * 4 + wc] = sq; }
.LBB0_1975:
	v_and_b32_e32 v161, 64, v196
	v_xor_b32_e32 v159, 16, v196
	v_add_u32_e32 v161, 64, v161
	v_cmp_lt_i32_e32 vcc, v159, v161
	v_lshl_add_u32 v160, s44, 8, v3
	v_lshl_or_b32 v158, s41, 8, v164
	v_cndmask_b32_e32 v159, v196, v159, vcc
	v_lshlrev_b32_e32 v167, 2, v159
	v_xor_b32_e32 v159, 32, v196
	v_cmp_lt_i32_e32 vcc, v159, v161
	v_ashrrev_i32_e32 v161, 31, v160
	v_lshlrev_b64 v[162:163], 12, v[160:161]
	v_cndmask_b32_e32 v159, v196, v159, vcc
	v_lshlrev_b32_e32 v166, 2, v159
	v_lshl_add_u64 v[162:163], s[56:57], 0, v[162:163]
	v_ashrrev_i32_e32 v159, 31, v158
	v_lshl_add_u64 v[162:163], v[158:159], 1, v[162:163]
	s_mov_b32 s101, 0
	global_load_dwordx4 v[212:215], v[162:163], off
	global_load_dwordx4 v[216:219], v[162:163], off offset:256
	s_mov_b32 s100, 0x10000
	v_lshl_add_u64 v[244:245], v[162:163], 0, s[100:101]
	global_load_dwordx4 v[220:223], v[244:245], off
	global_load_dwordx4 v[224:227], v[244:245], off offset:256
	s_mov_b32 s100, 0x20000
	v_lshl_add_u64 v[244:245], v[162:163], 0, s[100:101]
	global_load_dwordx4 v[228:231], v[244:245], off
	global_load_dwordx4 v[232:235], v[244:245], off offset:256
	s_mov_b32 s100, 0x30000
	v_lshl_add_u64 v[244:245], v[162:163], 0, s[100:101]
	global_load_dwordx4 v[236:239], v[244:245], off
	global_load_dwordx4 v[240:243], v[244:245], off offset:256
	s_waitcnt vmcnt(0)
	s_lshl_b32 s22, s41, 2
	s_ashr_i32 s23, s22, 31
	v_lshlrev_b32_e32 v172, 16, v212
	v_and_b32_e32 v173, 0xffff0000, v212
	v_lshlrev_b32_e32 v168, 16, v213
	v_and_b32_e32 v169, 0xffff0000, v213
	v_pk_add_f32 v[130:131], v[130:131], v[168:169]
	v_pk_add_f32 v[128:129], v[128:129], v[172:173]
	v_lshlrev_b32_e32 v168, 16, v214
	v_and_b32_e32 v169, 0xffff0000, v214
	v_lshlrev_b32_e32 v170, 16, v215
	v_and_b32_e32 v171, 0xffff0000, v215
	v_pk_add_f32 v[170:171], v[126:127], v[170:171]
	v_pk_add_f32 v[126:127], v[124:125], v[168:169]
	v_mul_f32_e32 v124, v129, v129
	v_mul_f32_e32 v125, v131, v131
	v_fmac_f32_e32 v124, v128, v128
	v_fmac_f32_e32 v125, v130, v130
	v_add_f32_e32 v124, v124, v125
	v_mul_f32_e32 v125, v127, v127
	v_fmac_f32_e32 v125, v126, v126
	v_add_f32_e32 v124, v125, v124
	v_mul_f32_e32 v125, v171, v171
	v_fmac_f32_e32 v125, v170, v170
	v_add_f32_e32 v168, v125, v124
	v_cvt_pk_bf16_f32 v124, v128, v129
	v_cvt_pk_bf16_f32 v125, v130, v131
	v_cvt_pk_bf16_f32 v126, v126, v127
	v_cvt_pk_bf16_f32 v127, v170, v171
	global_store_dwordx4 v[162:163], v[124:127], off
	v_lshlrev_b32_e32 v128, 16, v216
	v_and_b32_e32 v129, 0xffff0000, v216
	v_lshlrev_b32_e32 v124, 16, v217
	v_and_b32_e32 v125, 0xffff0000, v217
	v_pk_add_f32 v[122:123], v[122:123], v[124:125]
	v_pk_add_f32 v[120:121], v[120:121], v[128:129]
	v_lshlrev_b32_e32 v124, 16, v218
	v_and_b32_e32 v125, 0xffff0000, v218
	v_lshlrev_b32_e32 v126, 16, v219
	v_and_b32_e32 v127, 0xffff0000, v219
	v_pk_add_f32 v[126:127], v[118:119], v[126:127]
	v_pk_add_f32 v[118:119], v[116:117], v[124:125]
	v_mul_f32_e32 v116, v121, v121
	v_mul_f32_e32 v117, v123, v123
	v_fmac_f32_e32 v116, v120, v120
	v_fmac_f32_e32 v117, v122, v122
	v_add_f32_e32 v116, v116, v117
	v_mul_f32_e32 v117, v119, v119
	v_fmac_f32_e32 v117, v118, v118
	v_add_f32_e32 v116, v117, v116
	v_mul_f32_e32 v117, v127, v127
	v_fmac_f32_e32 v117, v126, v126
	v_add_f32_e32 v116, v117, v116
	v_add_f32_e32 v124, v168, v116
	v_cvt_pk_bf16_f32 v116, v120, v121
	v_cvt_pk_bf16_f32 v117, v122, v123
	v_cvt_pk_bf16_f32 v118, v118, v119
	v_cvt_pk_bf16_f32 v119, v126, v127
	global_store_dwordx4 v[162:163], v[116:119], off offset:256
	ds_bpermute_b32 v116, v167, v124
	s_waitcnt lgkmcnt(0)
	v_add_f32_e32 v116, v124, v116
	ds_bpermute_b32 v117, v166, v116
	s_and_saveexec_b64 s[24:25], s[8:9]
	s_cbranch_execz .LBB0_1977
	s_waitcnt lgkmcnt(0)
	v_add_f32_e32 v118, v116, v117
	v_lshlrev_b64 v[116:117], 7, v[160:161]
	v_lshl_add_u64 v[116:117], s[58:59], 0, v[116:117]
	v_lshl_add_u64 v[116:117], s[22:23], 2, v[116:117]
	s_lshl_b32 s80, s37, 2
	v_lshl_add_u64 v[116:117], v[116:117], 0, s[80:81]
	global_store_dword v[116:117], v118, off
.LBB0_1977:
	s_or_b64 exec, exec, s[24:25]
	v_or_b32_e32 v116, 16, v160
	s_waitcnt lgkmcnt(0)
	v_ashrrev_i32_e32 v117, 31, v116
	v_lshlrev_b64 v[118:119], 12, v[116:117]
	v_lshl_add_u64 v[118:119], s[56:57], 0, v[118:119]
	v_lshl_add_u64 v[118:119], v[158:159], 1, v[118:119]
	v_lshlrev_b32_e32 v124, 16, v220
	v_and_b32_e32 v125, 0xffff0000, v220
	v_lshlrev_b32_e32 v120, 16, v221
	v_and_b32_e32 v121, 0xffff0000, v221
	v_pk_add_f32 v[114:115], v[114:115], v[120:121]
	v_pk_add_f32 v[112:113], v[112:113], v[124:125]
	v_lshlrev_b32_e32 v120, 16, v222
	v_and_b32_e32 v121, 0xffff0000, v222
	v_lshlrev_b32_e32 v122, 16, v223
	v_and_b32_e32 v123, 0xffff0000, v223
	v_pk_add_f32 v[122:123], v[110:111], v[122:123]
	v_pk_add_f32 v[110:111], v[108:109], v[120:121]
	v_mul_f32_e32 v108, v113, v113
	v_mul_f32_e32 v109, v115, v115
	v_fmac_f32_e32 v108, v112, v112
	v_fmac_f32_e32 v109, v114, v114
	v_add_f32_e32 v108, v108, v109
	v_mul_f32_e32 v109, v111, v111
	v_fmac_f32_e32 v109, v110, v110
	v_add_f32_e32 v108, v109, v108
	v_mul_f32_e32 v109, v123, v123
	v_fmac_f32_e32 v109, v122, v122
	v_add_f32_e32 v120, v109, v108
	v_cvt_pk_bf16_f32 v108, v112, v113
	v_cvt_pk_bf16_f32 v109, v114, v115
	v_cvt_pk_bf16_f32 v110, v110, v111
	v_cvt_pk_bf16_f32 v111, v122, v123
	global_store_dwordx4 v[118:119], v[108:111], off
	v_lshlrev_b32_e32 v112, 16, v224
	v_and_b32_e32 v113, 0xffff0000, v224
	v_lshlrev_b32_e32 v108, 16, v225
	v_and_b32_e32 v109, 0xffff0000, v225
	v_pk_add_f32 v[106:107], v[106:107], v[108:109]
	v_pk_add_f32 v[104:105], v[104:105], v[112:113]
	v_lshlrev_b32_e32 v108, 16, v226
	v_and_b32_e32 v109, 0xffff0000, v226
	v_lshlrev_b32_e32 v110, 16, v227
	v_and_b32_e32 v111, 0xffff0000, v227
	v_pk_add_f32 v[110:111], v[102:103], v[110:111]
	v_pk_add_f32 v[102:103], v[100:101], v[108:109]
	v_mul_f32_e32 v100, v105, v105
	v_mul_f32_e32 v101, v107, v107
	v_fmac_f32_e32 v100, v104, v104
	v_fmac_f32_e32 v101, v106, v106
	v_add_f32_e32 v100, v100, v101
	v_mul_f32_e32 v101, v103, v103
	v_fmac_f32_e32 v101, v102, v102
	v_add_f32_e32 v100, v101, v100
	v_mul_f32_e32 v101, v111, v111
	v_fmac_f32_e32 v101, v110, v110
	v_add_f32_e32 v100, v101, v100
	v_add_f32_e32 v108, v120, v100
	v_cvt_pk_bf16_f32 v100, v104, v105
	v_cvt_pk_bf16_f32 v101, v106, v107
	v_cvt_pk_bf16_f32 v102, v102, v103
	v_cvt_pk_bf16_f32 v103, v110, v111
	global_store_dwordx4 v[118:119], v[100:103], off offset:256
	ds_bpermute_b32 v100, v167, v108
	s_waitcnt lgkmcnt(0)
	v_add_f32_e32 v100, v108, v100
	ds_bpermute_b32 v101, v166, v100
	s_and_saveexec_b64 s[24:25], s[8:9]
	s_cbranch_execz .LBB0_1979
	s_waitcnt lgkmcnt(0)
	v_add_f32_e32 v102, v100, v101
	v_lshlrev_b64 v[100:101], 7, v[116:117]
	v_lshl_add_u64 v[100:101], s[58:59], 0, v[100:101]
	v_lshl_add_u64 v[100:101], s[22:23], 2, v[100:101]
	s_lshl_b32 s80, s37, 2
	v_lshl_add_u64 v[100:101], v[100:101], 0, s[80:81]
	global_store_dword v[100:101], v102, off
; __device__ __forceinline__ unsigned cvt_pk_bf16(float lo, float hi) { const f32x2 v = {lo, hi}; return __builtin_bit_cast(unsigned, __builtin_convertvector(v, bf16x2_t)); }
; __device__ __forceinline__ float bf_lo(unsigned w) { return __uint_as_float(w << 16); }
; __device__ __forceinline__ float bf_hi(unsigned w) { return __uint_as_float(w & 0xffff0000u); }
;     __device__ __forceinline__ void operator()(const f32x4 (&acc)[2][2][4][2], const pg8::Unit& u, int wr, int wc, int fr, int fq) const {
;     ...
;             for (int m = 0; m < 4; ++m) { const size_t row = (size_t)(row0 + ai * 128 + m * 16); float sq = 0.f;
; #pragma unroll
;                 for (int bj = 0; bj < 2; ++bj) { const int col = col0 + bj * 128; bf16_t* xp = XB + row * D + col; const u32x4 xo = *(const u32x4*)xp;
;                     const f32x4 v0 = acc[ai][bj][m][0] + (f32x4){bf_lo(xo.x), bf_hi(xo.x), bf_lo(xo.y), bf_hi(xo.y)}, v1 = acc[ai][bj][m][1] + (f32x4){bf_lo(xo.z), bf_hi(xo.z), bf_lo(xo.w), bf_hi(xo.w)};
;                     sq += (v0[0] * v0[0] + v0[1] * v0[1]) + (v0[2] * v0[2] + v0[3] * v0[3]) + (v1[0] * v1[0] + v1[1] * v1[1]) + (v1[2] * v1[2] + v1[3] * v1[3]);
;                     u32x4 w; w.x = cvt_pk_bf16(v0[0], v0[1]); w.y = cvt_pk_bf16(v0[2], v0[3]); w.z = cvt_pk_bf16(v1[0], v1[1]); w.w = cvt_pk_bf16(v1[2], v1[3]);
;                     *(u32x4*)xp = w; }
;                 sq += __shfl_xor(sq, 16); sq += __shfl_xor(sq, 32);
;                 if (fq == 0) ssq[row * 32 + u.pn * 4 + wc] = sq; }
.LBB0_1979:
	s_or_b64 exec, exec, s[24:25]
	v_or_b32_e32 v100, 32, v160
	s_waitcnt lgkmcnt(0)
	v_ashrrev_i32_e32 v101, 31, v100
	v_lshlrev_b64 v[102:103], 12, v[100:101]
	v_lshl_add_u64 v[102:103], s[56:57], 0, v[102:103]
	v_lshl_add_u64 v[102:103], v[158:159], 1, v[102:103]
	v_lshlrev_b32_e32 v108, 16, v228
	v_and_b32_e32 v109, 0xffff0000, v228
	v_lshlrev_b32_e32 v104, 16, v229
	v_and_b32_e32 v105, 0xffff0000, v229
	v_pk_add_f32 v[98:99], v[98:99], v[104:105]
	v_pk_add_f32 v[96:97], v[96:97], v[108:109]
	v_lshlrev_b32_e32 v104, 16, v230
	v_and_b32_e32 v105, 0xffff0000, v230
	v_lshlrev_b32_e32 v106, 16, v231
	v_and_b32_e32 v107, 0xffff0000, v231
	v_pk_add_f32 v[106:107], v[94:95], v[106:107]
	v_pk_add_f32 v[94:95], v[92:93], v[104:105]
	v_mul_f32_e32 v92, v97, v97
	v_mul_f32_e32 v93, v99, v99
	v_fmac_f32_e32 v92, v96, v96
	v_fmac_f32_e32 v93, v98, v98
	v_add_f32_e32 v92, v92, v93
	v_mul_f32_e32 v93, v95, v95
	v_fmac_f32_e32 v93, v94, v94
	v_add_f32_e32 v92, v93, v92
	v_mul_f32_e32 v93, v107, v107
	v_fmac_f32_e32 v93, v106, v106
	v_add_f32_e32 v104, v93, v92
	v_cvt_pk_bf16_f32 v92, v96, v97
	v_cvt_pk_bf16_f32 v93, v98, v99
	v_cvt_pk_bf16_f32 v94, v94, v95
	v_cvt_pk_bf16_f32 v95, v106, v107
	global_store_dwordx4 v[102:103], v[92:95], off
	v_lshlrev_b32_e32 v96, 16, v232
	v_and_b32_e32 v97, 0xffff0000, v232
	v_lshlrev_b32_e32 v92, 16, v233
	v_and_b32_e32 v93, 0xffff0000, v233
	v_pk_add_f32 v[90:91], v[90:91], v[92:93]
	v_pk_add_f32 v[88:89], v[88:89], v[96:97]
	v_lshlrev_b32_e32 v92, 16, v234
	v_and_b32_e32 v93, 0xffff0000, v234
	v_lshlrev_b32_e32 v94, 16, v235
	v_and_b32_e32 v95, 0xffff0000, v235
	v_pk_add_f32 v[94:95], v[86:87], v[94:95]
	v_pk_add_f32 v[86:87], v[84:85], v[92:93]
	v_mul_f32_e32 v84, v89, v89
	v_mul_f32_e32 v85, v91, v91
	v_fmac_f32_e32 v84, v88, v88
	v_fmac_f32_e32 v85, v90, v90
	v_add_f32_e32 v84, v84, v85
	v_mul_f32_e32 v85, v87, v87
	v_fmac_f32_e32 v85, v86, v86
	v_add_f32_e32 v84, v85, v84
	v_mul_f32_e32 v85, v95, v95
	v_fmac_f32_e32 v85, v94, v94
	v_add_f32_e32 v84, v85, v84
	v_add_f32_e32 v92, v104, v84
	v_cvt_pk_bf16_f32 v84, v88, v89
	v_cvt_pk_bf16_f32 v85, v90, v91
	v_cvt_pk_bf16_f32 v86, v86, v87
	v_cvt_pk_bf16_f32 v87, v94, v95
	global_store_dwordx4 v[102:103], v[84:87], off offset:256
	ds_bpermute_b32 v84, v167, v92
	s_waitcnt lgkmcnt(0)
	v_add_f32_e32 v84, v92, v84
	ds_bpermute_b32 v85, v166, v84
	s_and_saveexec_b64 s[24:25], s[8:9]
	s_cbranch_execz .LBB0_1981
	s_waitcnt lgkmcnt(0)
	v_add_f32_e32 v86, v84, v85
	v_lshlrev_b64 v[84:85], 7, v[100:101]
	v_lshl_add_u64 v[84:85], s[58:59], 0, v[84:85]
	v_lshl_add_u64 v[84:85], s[22:23], 2, v[84:85]
	s_lshl_b32 s80, s37, 2
	v_lshl_add_u64 v[84:85], v[84:85], 0, s[80:81]
	global_store_dword v[84:85], v86, off
.LBB0_1981:
	s_or_b64 exec, exec, s[24:25]
	v_or_b32_e32 v84, 48, v160
	s_waitcnt lgkmcnt(0)
	v_ashrrev_i32_e32 v85, 31, v84
	v_lshlrev_b64 v[86:87], 12, v[84:85]
	v_lshl_add_u64 v[86:87], s[56:57], 0, v[86:87]
	v_lshl_add_u64 v[86:87], v[158:159], 1, v[86:87]
	v_lshlrev_b32_e32 v92, 16, v236
	v_and_b32_e32 v93, 0xffff0000, v236
	v_lshlrev_b32_e32 v88, 16, v237
	v_and_b32_e32 v89, 0xffff0000, v237
	v_pk_add_f32 v[82:83], v[82:83], v[88:89]
	v_pk_add_f32 v[80:81], v[80:81], v[92:93]
	v_lshlrev_b32_e32 v88, 16, v238
	v_and_b32_e32 v89, 0xffff0000, v238
	v_lshlrev_b32_e32 v90, 16, v239
	v_and_b32_e32 v91, 0xffff0000, v239
	v_pk_add_f32 v[90:91], v[78:79], v[90:91]
	v_pk_add_f32 v[78:79], v[76:77], v[88:89]
	v_mul_f32_e32 v76, v81, v81
	v_mul_f32_e32 v77, v83, v83
	v_fmac_f32_e32 v76, v80, v80
	v_fmac_f32_e32 v77, v82, v82
	v_add_f32_e32 v76, v76, v77
	v_mul_f32_e32 v77, v79, v79
	v_fmac_f32_e32 v77, v78, v78
	v_add_f32_e32 v76, v77, v76
	v_mul_f32_e32 v77, v91, v91
	v_fmac_f32_e32 v77, v90, v90
	v_add_f32_e32 v88, v77, v76
	v_cvt_pk_bf16_f32 v76, v80, v81
	v_cvt_pk_bf16_f32 v77, v82, v83
	v_cvt_pk_bf16_f32 v78, v78, v79
	v_cvt_pk_bf16_f32 v79, v90, v91
	global_store_dwordx4 v[86:87], v[76:79], off
	v_lshlrev_b32_e32 v80, 16, v240
	v_and_b32_e32 v81, 0xffff0000, v240
	v_lshlrev_b32_e32 v76, 16, v241
	v_and_b32_e32 v77, 0xffff0000, v241
	v_pk_add_f32 v[74:75], v[74:75], v[76:77]
	v_pk_add_f32 v[72:73], v[72:73], v[80:81]
	v_lshlrev_b32_e32 v76, 16, v242
	v_and_b32_e32 v77, 0xffff0000, v242
	v_lshlrev_b32_e32 v78, 16, v243
	v_and_b32_e32 v79, 0xffff0000, v243
	v_pk_add_f32 v[78:79], v[70:71], v[78:79]
	v_pk_add_f32 v[70:71], v[68:69], v[76:77]
	v_mul_f32_e32 v68, v73, v73
	v_mul_f32_e32 v69, v75, v75
	v_fmac_f32_e32 v68, v72, v72
	v_fmac_f32_e32 v69, v74, v74
	v_add_f32_e32 v68, v68, v69
	v_mul_f32_e32 v69, v71, v71
	v_fmac_f32_e32 v69, v70, v70
	v_add_f32_e32 v68, v69, v68
	v_mul_f32_e32 v69, v79, v79
	v_fmac_f32_e32 v69, v78, v78
	v_add_f32_e32 v68, v69, v68
	v_add_f32_e32 v76, v88, v68
	v_cvt_pk_bf16_f32 v68, v72, v73
	v_cvt_pk_bf16_f32 v69, v74, v75
	v_cvt_pk_bf16_f32 v70, v70, v71
	v_cvt_pk_bf16_f32 v71, v78, v79
	global_store_dwordx4 v[86:87], v[68:71], off offset:256
	ds_bpermute_b32 v68, v167, v76
	s_waitcnt lgkmcnt(0)
	v_add_f32_e32 v68, v76, v68
	ds_bpermute_b32 v69, v166, v68
	s_and_saveexec_b64 s[24:25], s[8:9]
	s_cbranch_execz .LBB0_1983
	s_waitcnt lgkmcnt(0)
	v_add_f32_e32 v70, v68, v69
	v_lshlrev_b64 v[68:69], 7, v[84:85]
	v_lshl_add_u64 v[68:69], s[58:59], 0, v[68:69]
	v_lshl_add_u64 v[68:69], s[22:23], 2, v[68:69]
	s_lshl_b32 s80, s37, 2
	v_lshl_add_u64 v[68:69], v[68:69], 0, s[80:81]
	global_store_dword v[68:69], v70, off
; __device__ __forceinline__ unsigned cvt_pk_bf16(float lo, float hi) { const f32x2 v = {lo, hi}; return __builtin_bit_cast(unsigned, __builtin_convertvector(v, bf16x2_t)); }
; __device__ __forceinline__ float bf_lo(unsigned w) { return __uint_as_float(w << 16); }
; __device__ __forceinline__ float bf_hi(unsigned w) { return __uint_as_float(w & 0xffff0000u); }
;     __device__ __forceinline__ void operator()(const f32x4 (&acc)[2][2][4][2], const pg8::Unit& u, int wr, int wc, int fr, int fq) const {
;         const int row0 = u.pm * 256 + wr * 64 + fr, col0 = u.pn * 256 + wc * 32 + 8 * fq;
; #pragma unroll
;         for (int ai = 0; ai < 2; ++ai)
; #pragma unroll
;             for (int m = 0; m < 4; ++m) { const size_t row = (size_t)(row0 + ai * 128 + m * 16); float sq = 0.f;
; #pragma unroll
;                 for (int bj = 0; bj < 2; ++bj) { const int col = col0 + bj * 128; bf16_t* xp = XB + row * D + col; const u32x4 xo = *(const u32x4*)xp;
;                     const f32x4 v0 = acc[ai][bj][m][0] + (f32x4){bf_lo(xo.x), bf_hi(xo.x), bf_lo(xo.y), bf_hi(xo.y)}, v1 = acc[ai][bj][m][1] + (f32x4){bf_lo(xo.z), bf_hi(xo.z), bf_lo(xo.w), bf_hi(xo.w)};
;                     sq += (v0[0] * v0[0] + v0[1] * v0[1]) + (v0[2] * v0[2] + v0[3] * v0[3]) + (v1[0] * v1[0] + v1[1] * v1[1]) + (v1[2] * v1[2] + v1[3] * v1[3]);
;                     u32x4 w; w.x = cvt_pk_bf16(v0[0], v0[1]); w.y = cvt_pk_bf16(v0[2], v0[3]); w.z = cvt_pk_bf16(v1[0], v1[1]); w.w = cvt_pk_bf16(v1[2], v1[3]);
;                     *(u32x4*)xp = w; }
;                 sq += __shfl_xor(sq, 16); sq += __shfl_xor(sq, 32);
;                 if (fq == 0) ssq[row * 32 + u.pn * 4 + wc] = sq; }
.LBB0_1983:
	s_or_b64 exec, exec, s[24:25]
	v_add_u32_e32 v68, 0x80, v160
	s_waitcnt lgkmcnt(0)
	v_ashrrev_i32_e32 v69, 31, v68
	v_lshlrev_b64 v[70:71], 12, v[68:69]
	v_lshl_add_u64 v[70:71], s[56:57], 0, v[70:71]
	v_lshl_add_u64 v[70:71], v[158:159], 1, v[70:71]
	s_mov_b32 s101, 0
	global_load_dwordx4 v[212:215], v[70:71], off
	global_load_dwordx4 v[216:219], v[70:71], off offset:256
	s_mov_b32 s100, 0x10000
	v_lshl_add_u64 v[244:245], v[70:71], 0, s[100:101]
	global_load_dwordx4 v[220:223], v[244:245], off
	global_load_dwordx4 v[224:227], v[244:245], off offset:256
	s_mov_b32 s100, 0x20000
	v_lshl_add_u64 v[244:245], v[70:71], 0, s[100:101]
	global_load_dwordx4 v[228:231], v[244:245], off
	global_load_dwordx4 v[232:235], v[244:245], off offset:256
	s_mov_b32 s100, 0x30000
	v_lshl_add_u64 v[244:245], v[70:71], 0, s[100:101]
	global_load_dwordx4 v[236:239], v[244:245], off
	global_load_dwordx4 v[240:243], v[244:245], off offset:256
	s_waitcnt vmcnt(0)
	v_lshlrev_b32_e32 v76, 16, v212
	v_and_b32_e32 v77, 0xffff0000, v212
	v_lshlrev_b32_e32 v72, 16, v213
	v_and_b32_e32 v73, 0xffff0000, v213
	v_pk_add_f32 v[66:67], v[66:67], v[72:73]
	v_pk_add_f32 v[64:65], v[64:65], v[76:77]
	v_lshlrev_b32_e32 v72, 16, v214
	v_and_b32_e32 v73, 0xffff0000, v214
	v_lshlrev_b32_e32 v74, 16, v215
	v_and_b32_e32 v75, 0xffff0000, v215
	v_pk_add_f32 v[74:75], v[62:63], v[74:75]
	v_pk_add_f32 v[62:63], v[60:61], v[72:73]
	v_mul_f32_e32 v60, v65, v65
	v_mul_f32_e32 v61, v67, v67
	v_fmac_f32_e32 v60, v64, v64
	v_fmac_f32_e32 v61, v66, v66
	v_add_f32_e32 v60, v60, v61
	v_mul_f32_e32 v61, v63, v63
	v_fmac_f32_e32 v61, v62, v62
	v_add_f32_e32 v60, v61, v60
	v_mul_f32_e32 v61, v75, v75
	v_fmac_f32_e32 v61, v74, v74
	v_add_f32_e32 v72, v61, v60
	v_cvt_pk_bf16_f32 v60, v64, v65
	v_cvt_pk_bf16_f32 v61, v66, v67
	v_cvt_pk_bf16_f32 v62, v62, v63
	v_cvt_pk_bf16_f32 v63, v74, v75
	global_store_dwordx4 v[70:71], v[60:63], off
	v_lshlrev_b32_e32 v64, 16, v216
	v_and_b32_e32 v65, 0xffff0000, v216
	v_lshlrev_b32_e32 v60, 16, v217
	v_and_b32_e32 v61, 0xffff0000, v217
	v_pk_add_f32 v[58:59], v[58:59], v[60:61]
	v_pk_add_f32 v[56:57], v[56:57], v[64:65]
	v_lshlrev_b32_e32 v60, 16, v218
	v_and_b32_e32 v61, 0xffff0000, v218
	v_lshlrev_b32_e32 v62, 16, v219
	v_and_b32_e32 v63, 0xffff0000, v219
	v_pk_add_f32 v[62:63], v[54:55], v[62:63]
	v_pk_add_f32 v[54:55], v[52:53], v[60:61]
	v_mul_f32_e32 v52, v57, v57
	v_mul_f32_e32 v53, v59, v59
	v_fmac_f32_e32 v52, v56, v56
	v_fmac_f32_e32 v53, v58, v58
	v_add_f32_e32 v52, v52, v53
	v_mul_f32_e32 v53, v55, v55
	v_fmac_f32_e32 v53, v54, v54
	v_add_f32_e32 v52, v53, v52
	v_mul_f32_e32 v53, v63, v63
	v_fmac_f32_e32 v53, v62, v62
	v_add_f32_e32 v52, v53, v52
	v_add_f32_e32 v60, v72, v52
	v_cvt_pk_bf16_f32 v52, v56, v57
	v_cvt_pk_bf16_f32 v53, v58, v59
	v_cvt_pk_bf16_f32 v54, v54, v55
	v_cvt_pk_bf16_f32 v55, v62, v63
	global_store_dwordx4 v[70:71], v[52:55], off offset:256
	ds_bpermute_b32 v52, v167, v60
	s_waitcnt lgkmcnt(0)
	v_add_f32_e32 v52, v60, v52
	ds_bpermute_b32 v53, v166, v52
	s_and_saveexec_b64 s[24:25], s[8:9]
	s_cbranch_execz .LBB0_1985
	s_waitcnt lgkmcnt(0)
	v_add_f32_e32 v54, v52, v53
	v_lshlrev_b64 v[52:53], 7, v[68:69]
	v_lshl_add_u64 v[52:53], s[58:59], 0, v[52:53]
	v_lshl_add_u64 v[52:53], s[22:23], 2, v[52:53]
	s_lshl_b32 s80, s37, 2
	v_lshl_add_u64 v[52:53], v[52:53], 0, s[80:81]
	global_store_dword v[52:53], v54, off
.LBB0_1985:
	s_or_b64 exec, exec, s[24:25]
	v_add_u32_e32 v52, 0x90, v160
	s_waitcnt lgkmcnt(0)
	v_ashrrev_i32_e32 v53, 31, v52
	v_lshlrev_b64 v[54:55], 12, v[52:53]
	v_lshl_add_u64 v[54:55], s[56:57], 0, v[54:55]
	v_lshl_add_u64 v[54:55], v[158:159], 1, v[54:55]
	v_lshlrev_b32_e32 v60, 16, v220
	v_and_b32_e32 v61, 0xffff0000, v220
	v_lshlrev_b32_e32 v56, 16, v221
	v_and_b32_e32 v57, 0xffff0000, v221
	v_pk_add_f32 v[50:51], v[50:51], v[56:57]
	v_pk_add_f32 v[48:49], v[48:49], v[60:61]
	v_lshlrev_b32_e32 v56, 16, v222
	v_and_b32_e32 v57, 0xffff0000, v222
	v_lshlrev_b32_e32 v58, 16, v223
	v_and_b32_e32 v59, 0xffff0000, v223
	v_pk_add_f32 v[58:59], v[46:47], v[58:59]
	v_pk_add_f32 v[46:47], v[44:45], v[56:57]
	v_mul_f32_e32 v44, v49, v49
	v_mul_f32_e32 v45, v51, v51
	v_fmac_f32_e32 v44, v48, v48
	v_fmac_f32_e32 v45, v50, v50
	v_add_f32_e32 v44, v44, v45
	v_mul_f32_e32 v45, v47, v47
	v_fmac_f32_e32 v45, v46, v46
	v_add_f32_e32 v44, v45, v44
	v_mul_f32_e32 v45, v59, v59
	v_fmac_f32_e32 v45, v58, v58
	v_add_f32_e32 v56, v45, v44
	v_cvt_pk_bf16_f32 v44, v48, v49
	v_cvt_pk_bf16_f32 v45, v50, v51
	v_cvt_pk_bf16_f32 v46, v46, v47
	v_cvt_pk_bf16_f32 v47, v58, v59
	global_store_dwordx4 v[54:55], v[44:47], off
	v_lshlrev_b32_e32 v48, 16, v224
	v_and_b32_e32 v49, 0xffff0000, v224
	v_lshlrev_b32_e32 v44, 16, v225
	v_and_b32_e32 v45, 0xffff0000, v225
	v_pk_add_f32 v[42:43], v[42:43], v[44:45]
	v_pk_add_f32 v[40:41], v[40:41], v[48:49]
	v_lshlrev_b32_e32 v44, 16, v226
	v_and_b32_e32 v45, 0xffff0000, v226
	v_lshlrev_b32_e32 v46, 16, v227
	v_and_b32_e32 v47, 0xffff0000, v227
	v_pk_add_f32 v[46:47], v[38:39], v[46:47]
	v_pk_add_f32 v[38:39], v[36:37], v[44:45]
	v_mul_f32_e32 v36, v41, v41
	v_mul_f32_e32 v37, v43, v43
	v_fmac_f32_e32 v36, v40, v40
	v_fmac_f32_e32 v37, v42, v42
	v_add_f32_e32 v36, v36, v37
	v_mul_f32_e32 v37, v39, v39
	v_fmac_f32_e32 v37, v38, v38
	v_add_f32_e32 v36, v37, v36
	v_mul_f32_e32 v37, v47, v47
	v_fmac_f32_e32 v37, v46, v46
	v_add_f32_e32 v36, v37, v36
	v_add_f32_e32 v44, v56, v36
	v_cvt_pk_bf16_f32 v36, v40, v41
	v_cvt_pk_bf16_f32 v37, v42, v43
	v_cvt_pk_bf16_f32 v38, v38, v39
	v_cvt_pk_bf16_f32 v39, v46, v47
	global_store_dwordx4 v[54:55], v[36:39], off offset:256
	ds_bpermute_b32 v36, v167, v44
	s_waitcnt lgkmcnt(0)
	v_add_f32_e32 v36, v44, v36
	ds_bpermute_b32 v37, v166, v36
	s_and_saveexec_b64 s[24:25], s[8:9]
	s_cbranch_execz .LBB0_1987
	s_waitcnt lgkmcnt(0)
	v_add_f32_e32 v38, v36, v37
	v_lshlrev_b64 v[36:37], 7, v[52:53]
	v_lshl_add_u64 v[36:37], s[58:59], 0, v[36:37]
	v_lshl_add_u64 v[36:37], s[22:23], 2, v[36:37]
	s_lshl_b32 s80, s37, 2
	v_lshl_add_u64 v[36:37], v[36:37], 0, s[80:81]
	global_store_dword v[36:37], v38, off
; __device__ __forceinline__ unsigned cvt_pk_bf16(float lo, float hi) { const f32x2 v = {lo, hi}; return __builtin_bit_cast(unsigned, __builtin_convertvector(v, bf16x2_t)); }
; __device__ __forceinline__ float bf_lo(unsigned w) { return __uint_as_float(w << 16); }
; __device__ __forceinline__ float bf_hi(unsigned w) { return __uint_as_float(w & 0xffff0000u); }
;     __device__ __forceinline__ void operator()(const f32x4 (&acc)[2][2][4][2], const pg8::Unit& u, int wr, int wc, int fr, int fq) const {
;     ...
;             for (int m = 0; m < 4; ++m) { const size_t row = (size_t)(row0 + ai * 128 + m * 16); float sq = 0.f;
; #pragma unroll
;                 for (int bj = 0; bj < 2; ++bj) { const int col = col0 + bj * 128; bf16_t* xp = XB + row * D + col; const u32x4 xo = *(const u32x4*)xp;
;                     const f32x4 v0 = acc[ai][bj][m][0] + (f32x4){bf_lo(xo.x), bf_hi(xo.x), bf_lo(xo.y), bf_hi(xo.y)}, v1 = acc[ai][bj][m][1] + (f32x4){bf_lo(xo.z), bf_hi(xo.z), bf_lo(xo.w), bf_hi(xo.w)};
;                     sq += (v0[0] * v0[0] + v0[1] * v0[1]) + (v0[2] * v0[2] + v0[3] * v0[3]) + (v1[0] * v1[0] + v1[1] * v1[1]) + (v1[2] * v1[2] + v1[3] * v1[3]);
;                     u32x4 w; w.x = cvt_pk_bf16(v0[0], v0[1]); w.y = cvt_pk_bf16(v0[2], v0[3]); w.z = cvt_pk_bf16(v1[0], v1[1]); w.w = cvt_pk_bf16(v1[2], v1[3]);
;                     *(u32x4*)xp = w; }
;                 sq += __shfl_xor(sq, 16); sq += __shfl_xor(sq, 32);
;                 if (fq == 0) ssq[row * 32 + u.pn * 4 + wc] = sq; }
.LBB0_1987:
	s_or_b64 exec, exec, s[24:25]
	v_add_u32_e32 v36, 0xa0, v160
	s_waitcnt lgkmcnt(0)
	v_ashrrev_i32_e32 v37, 31, v36
	v_lshlrev_b64 v[38:39], 12, v[36:37]
	v_lshl_add_u64 v[38:39], s[56:57], 0, v[38:39]
	v_lshl_add_u64 v[38:39], v[158:159], 1, v[38:39]
	v_lshlrev_b32_e32 v44, 16, v228
	v_and_b32_e32 v45, 0xffff0000, v228
	v_lshlrev_b32_e32 v40, 16, v229
	v_and_b32_e32 v41, 0xffff0000, v229
	v_pk_add_f32 v[34:35], v[34:35], v[40:41]
	v_pk_add_f32 v[32:33], v[32:33], v[44:45]
	v_lshlrev_b32_e32 v40, 16, v230
	v_and_b32_e32 v41, 0xffff0000, v230
	v_lshlrev_b32_e32 v42, 16, v231
	v_and_b32_e32 v43, 0xffff0000, v231
	v_pk_add_f32 v[42:43], v[30:31], v[42:43]
	v_pk_add_f32 v[30:31], v[28:29], v[40:41]
	v_mul_f32_e32 v28, v33, v33
	v_mul_f32_e32 v29, v35, v35
	v_fmac_f32_e32 v28, v32, v32
	v_fmac_f32_e32 v29, v34, v34
	v_add_f32_e32 v28, v28, v29
	v_mul_f32_e32 v29, v31, v31
	v_fmac_f32_e32 v29, v30, v30
	v_add_f32_e32 v28, v29, v28
	v_mul_f32_e32 v29, v43, v43
	v_fmac_f32_e32 v29, v42, v42
	v_add_f32_e32 v40, v29, v28
	v_cvt_pk_bf16_f32 v28, v32, v33
	v_cvt_pk_bf16_f32 v29, v34, v35
	v_cvt_pk_bf16_f32 v30, v30, v31
	v_cvt_pk_bf16_f32 v31, v42, v43
	global_store_dwordx4 v[38:39], v[28:31], off
	v_lshlrev_b32_e32 v32, 16, v232
	v_and_b32_e32 v33, 0xffff0000, v232
	v_lshlrev_b32_e32 v28, 16, v233
	v_and_b32_e32 v29, 0xffff0000, v233
	v_pk_add_f32 v[26:27], v[26:27], v[28:29]
	v_pk_add_f32 v[24:25], v[24:25], v[32:33]
	v_lshlrev_b32_e32 v28, 16, v234
	v_and_b32_e32 v29, 0xffff0000, v234
	v_lshlrev_b32_e32 v30, 16, v235
	v_and_b32_e32 v31, 0xffff0000, v235
	v_pk_add_f32 v[30:31], v[22:23], v[30:31]
	v_pk_add_f32 v[22:23], v[20:21], v[28:29]
	v_mul_f32_e32 v20, v25, v25
	v_mul_f32_e32 v21, v27, v27
	v_fmac_f32_e32 v20, v24, v24
	v_fmac_f32_e32 v21, v26, v26
	v_add_f32_e32 v20, v20, v21
	v_mul_f32_e32 v21, v23, v23
	v_fmac_f32_e32 v21, v22, v22
	v_add_f32_e32 v20, v21, v20
	v_mul_f32_e32 v21, v31, v31
	v_fmac_f32_e32 v21, v30, v30
	v_add_f32_e32 v20, v21, v20
	v_add_f32_e32 v28, v40, v20
	v_cvt_pk_bf16_f32 v20, v24, v25
	v_cvt_pk_bf16_f32 v21, v26, v27
	v_cvt_pk_bf16_f32 v22, v22, v23
	v_cvt_pk_bf16_f32 v23, v30, v31
	global_store_dwordx4 v[38:39], v[20:23], off offset:256
	ds_bpermute_b32 v20, v167, v28
	s_waitcnt lgkmcnt(0)
	v_add_f32_e32 v20, v28, v20
	ds_bpermute_b32 v21, v166, v20
	s_and_saveexec_b64 s[24:25], s[8:9]
	s_cbranch_execz .LBB0_1989
	s_waitcnt lgkmcnt(0)
	v_add_f32_e32 v22, v20, v21
	v_lshlrev_b64 v[20:21], 7, v[36:37]
	v_lshl_add_u64 v[20:21], s[58:59], 0, v[20:21]
	v_lshl_add_u64 v[20:21], s[22:23], 2, v[20:21]
	s_lshl_b32 s80, s37, 2
	v_lshl_add_u64 v[20:21], v[20:21], 0, s[80:81]
	global_store_dword v[20:21], v22, off
.LBB0_1989:
	s_or_b64 exec, exec, s[24:25]
	v_add_u32_e32 v20, 0xb0, v160
	s_waitcnt lgkmcnt(0)
	v_ashrrev_i32_e32 v21, 31, v20
	v_lshlrev_b64 v[22:23], 12, v[20:21]
	v_lshl_add_u64 v[22:23], s[56:57], 0, v[22:23]
	v_lshl_add_u64 v[22:23], v[158:159], 1, v[22:23]
	v_lshlrev_b32_e32 v28, 16, v236
	v_and_b32_e32 v29, 0xffff0000, v236
	v_lshlrev_b32_e32 v24, 16, v237
	v_and_b32_e32 v25, 0xffff0000, v237
	v_pk_add_f32 v[18:19], v[18:19], v[24:25]
	v_pk_add_f32 v[16:17], v[16:17], v[28:29]
	v_lshlrev_b32_e32 v24, 16, v238
	v_and_b32_e32 v25, 0xffff0000, v238
	v_lshlrev_b32_e32 v26, 16, v239
	v_and_b32_e32 v27, 0xffff0000, v239
	v_pk_add_f32 v[26:27], v[14:15], v[26:27]
	v_pk_add_f32 v[14:15], v[12:13], v[24:25]
	v_mul_f32_e32 v12, v17, v17
	v_mul_f32_e32 v13, v19, v19
	v_fmac_f32_e32 v12, v16, v16
	v_fmac_f32_e32 v13, v18, v18
	v_add_f32_e32 v12, v12, v13
	v_mul_f32_e32 v13, v15, v15
	v_fmac_f32_e32 v13, v14, v14
	v_add_f32_e32 v12, v13, v12
	v_mul_f32_e32 v13, v27, v27
	v_fmac_f32_e32 v13, v26, v26
	v_add_f32_e32 v24, v13, v12
	v_cvt_pk_bf16_f32 v12, v16, v17
	v_cvt_pk_bf16_f32 v13, v18, v19
	v_cvt_pk_bf16_f32 v14, v14, v15
	v_cvt_pk_bf16_f32 v15, v26, v27
	global_store_dwordx4 v[22:23], v[12:15], off
	v_lshlrev_b32_e32 v16, 16, v240
	v_and_b32_e32 v17, 0xffff0000, v240
	v_lshlrev_b32_e32 v12, 16, v241
	v_and_b32_e32 v13, 0xffff0000, v241
	v_pk_add_f32 v[10:11], v[10:11], v[12:13]
	v_pk_add_f32 v[8:9], v[8:9], v[16:17]
	v_lshlrev_b32_e32 v12, 16, v242
	v_and_b32_e32 v13, 0xffff0000, v242
	v_lshlrev_b32_e32 v14, 16, v243
	v_and_b32_e32 v15, 0xffff0000, v243
	v_pk_add_f32 v[14:15], v[6:7], v[14:15]
	v_pk_add_f32 v[6:7], v[4:5], v[12:13]
	v_mul_f32_e32 v4, v9, v9
	v_mul_f32_e32 v5, v11, v11
	v_fmac_f32_e32 v4, v8, v8
	v_fmac_f32_e32 v5, v10, v10
	v_add_f32_e32 v4, v4, v5
	v_mul_f32_e32 v5, v7, v7
	v_fmac_f32_e32 v5, v6, v6
	v_add_f32_e32 v4, v5, v4
	v_mul_f32_e32 v5, v15, v15
	v_fmac_f32_e32 v5, v14, v14
	v_add_f32_e32 v4, v5, v4
	v_add_f32_e32 v12, v24, v4
	v_cvt_pk_bf16_f32 v4, v8, v9
	v_cvt_pk_bf16_f32 v5, v10, v11
	v_cvt_pk_bf16_f32 v6, v6, v7
	v_cvt_pk_bf16_f32 v7, v14, v15
	global_store_dwordx4 v[22:23], v[4:7], off offset:256
	ds_bpermute_b32 v4, v167, v12
	s_waitcnt lgkmcnt(0)
	v_add_f32_e32 v4, v12, v4
	ds_bpermute_b32 v5, v166, v4
	s_and_saveexec_b64 s[24:25], s[8:9]
	s_cbranch_execz .LBB0_1991
	s_waitcnt lgkmcnt(0)
	v_add_f32_e32 v6, v4, v5
	v_lshlrev_b64 v[4:5], 7, v[20:21]
	v_lshl_add_u64 v[4:5], s[58:59], 0, v[4:5]
	v_lshl_add_u64 v[4:5], s[22:23], 2, v[4:5]
	s_lshl_b32 s80, s37, 2
	v_lshl_add_u64 v[4:5], v[4:5], 0, s[80:81]
	global_store_dword v[4:5], v6, off
